# strategy 6.1: K-loop loop-back SALU block issued in the shadow of the last MFMA cluster (all six GEMM mainloops)
# speedup vs baseline: 1.0075x; 1.0075x over previous
.LBB0_504:
	ds_read_b128 v[144:147], v153
	ds_read_b128 v[158:161], v153 offset:1024
	ds_read_b128 v[162:165], v153 offset:2048
	ds_read_b128 v[166:169], v153 offset:3072
	ds_read_b128 v[170:173], v154
	ds_read_b128 v[174:177], v154 offset:1024
	ds_read_b128 v[178:181], v154 offset:2048
	ds_read_b128 v[184:187], v154 offset:3072
	s_add_u32 s22, s20, 0xfff80080
	s_addc_u32 s23, s21, -1
	s_cmp_eq_u32 s46, 28
	s_cselect_b32 s25, s13, s23
	s_cselect_b32 s24, s42, s22
	s_cselect_b32 s23, s3, s45
	s_cselect_b32 s22, s43, s44
	v_lshl_add_u64 v[148:149], s[20:21], 0, v[136:137]
	s_add_i32 m0, s28, 0xc000
	ds_read_b128 v[190:193], v155
	ds_read_b128 v[194:197], v155 offset:1024
	ds_read_b128 v[198:201], v155 offset:2048
	ds_read_b128 v[202:205], v155 offset:3072
	ds_read_b128 v[206:209], v155 offset:4096
	ds_read_b128 v[210:213], v155 offset:5120
	ds_read_b128 v[214:217], v155 offset:6144
	ds_read_b128 v[218:221], v155 offset:7168
	global_load_lds_dwordx4 v[148:149], off
	v_lshl_add_u64 v[148:149], s[20:21], 0, v[138:139]
	s_add_i32 m0, s28, 0xe000
	s_nop 0
	global_load_lds_dwordx4 v[148:149], off
	s_waitcnt vmcnt(8)
	s_waitcnt lgkmcnt(0)
	s_barrier
	s_setprio 1
	s_waitcnt lgkmcnt(0)
	v_mfma_f32_16x16x32_bf16 v[124:127], v[144:147], v[190:193], v[124:127]
	v_mfma_f32_16x16x32_bf16 v[116:119], v[162:165], v[190:193], v[116:119]
	v_mfma_f32_16x16x32_bf16 v[108:111], v[144:147], v[198:201], v[108:111]
	v_mfma_f32_16x16x32_bf16 v[100:103], v[162:165], v[198:201], v[100:103]
	v_mfma_f32_16x16x32_bf16 v[92:95], v[144:147], v[206:209], v[92:95]
	v_mfma_f32_16x16x32_bf16 v[84:87], v[162:165], v[206:209], v[84:87]
	v_mfma_f32_16x16x32_bf16 v[76:79], v[144:147], v[214:217], v[76:79]
	v_mfma_f32_16x16x32_bf16 v[68:71], v[162:165], v[214:217], v[68:71]
	v_mfma_f32_16x16x32_bf16 v[124:127], v[158:161], v[194:197], v[124:127]
	v_mfma_f32_16x16x32_bf16 v[116:119], v[166:169], v[194:197], v[116:119]
	v_mfma_f32_16x16x32_bf16 v[108:111], v[158:161], v[202:205], v[108:111]
	v_mfma_f32_16x16x32_bf16 v[100:103], v[166:169], v[202:205], v[100:103]
	v_mfma_f32_16x16x32_bf16 v[92:95], v[158:161], v[210:213], v[92:95]
	v_mfma_f32_16x16x32_bf16 v[84:87], v[166:169], v[210:213], v[84:87]
	v_mfma_f32_16x16x32_bf16 v[76:79], v[158:161], v[218:221], v[76:79]
	v_mfma_f32_16x16x32_bf16 v[68:71], v[166:169], v[218:221], v[68:71]
	s_setprio 0
	s_setprio 1
	v_mfma_f32_16x16x32_bf16 v[120:123], v[170:173], v[190:193], v[120:123]
	v_mfma_f32_16x16x32_bf16 v[112:115], v[178:181], v[190:193], v[112:115]
	v_mfma_f32_16x16x32_bf16 v[104:107], v[170:173], v[198:201], v[104:107]
	v_mfma_f32_16x16x32_bf16 v[96:99], v[178:181], v[198:201], v[96:99]
	v_mfma_f32_16x16x32_bf16 v[88:91], v[170:173], v[206:209], v[88:91]
	v_mfma_f32_16x16x32_bf16 v[80:83], v[178:181], v[206:209], v[80:83]
	v_mfma_f32_16x16x32_bf16 v[72:75], v[170:173], v[214:217], v[72:75]
	v_mfma_f32_16x16x32_bf16 v[64:67], v[178:181], v[214:217], v[64:67]
	v_mfma_f32_16x16x32_bf16 v[120:123], v[174:177], v[194:197], v[120:123]
	v_mfma_f32_16x16x32_bf16 v[112:115], v[184:187], v[194:197], v[112:115]
	v_mfma_f32_16x16x32_bf16 v[104:107], v[174:177], v[202:205], v[104:107]
	v_mfma_f32_16x16x32_bf16 v[96:99], v[184:187], v[202:205], v[96:99]
	v_mfma_f32_16x16x32_bf16 v[88:91], v[174:177], v[210:213], v[88:91]
	v_mfma_f32_16x16x32_bf16 v[80:83], v[184:187], v[210:213], v[80:83]
	v_mfma_f32_16x16x32_bf16 v[72:75], v[174:177], v[218:221], v[72:75]
	v_mfma_f32_16x16x32_bf16 v[64:67], v[184:187], v[218:221], v[64:67]
	s_setprio 0
	s_barrier
	s_add_i32 s47, s38, s27
	v_lshl_add_u64 v[148:149], s[22:23], 0, v[130:131]
	s_mov_b32 m0, s47
	ds_read_b128 v[190:193], v155 offset:16384
	ds_read_b128 v[194:197], v155 offset:17408
	ds_read_b128 v[198:201], v155 offset:18432
	ds_read_b128 v[202:205], v155 offset:19456
	ds_read_b128 v[206:209], v155 offset:20480
	ds_read_b128 v[210:213], v155 offset:21504
	ds_read_b128 v[214:217], v155 offset:22528
	ds_read_b128 v[218:221], v155 offset:23552
	global_load_lds_dwordx4 v[148:149], off
	s_add_i32 m0, s47, 0x2000
	s_add_u32 s48, s22, 0x80000
	v_lshl_add_u64 v[222:223], s[22:23], 0, v[134:135]
	s_addc_u32 s49, s23, 0
	s_add_i32 s47, s39, s27
	global_load_lds_dwordx4 v[222:223], off
	v_lshl_add_u64 v[224:225], s[48:49], 0, v[130:131]
	s_mov_b32 m0, s47
	v_lshl_add_u64 v[226:227], s[24:25], 0, v[132:133]
	global_load_lds_dwordx4 v[224:225], off
	v_lshl_add_u64 v[224:225], s[48:49], 0, v[134:135]
	s_add_i32 m0, s47, 0x2000
	s_nop 0
	global_load_lds_dwordx4 v[224:225], off
	v_lshl_add_u64 v[224:225], s[24:25], 0, v[128:129]
	s_mov_b32 m0, s28
	s_nop 0
	global_load_lds_dwordx4 v[224:225], off
	s_mov_b32 m0, s29
	s_nop 0
	global_load_lds_dwordx4 v[226:227], off
	s_waitcnt vmcnt(8)
	s_waitcnt lgkmcnt(0)
	s_barrier
	s_setprio 1
	s_waitcnt lgkmcnt(0)
	v_mfma_f32_16x16x32_bf16 v[60:63], v[144:147], v[190:193], v[60:63]
	v_mfma_f32_16x16x32_bf16 v[52:55], v[162:165], v[190:193], v[52:55]
	v_mfma_f32_16x16x32_bf16 v[44:47], v[144:147], v[198:201], v[44:47]
	v_mfma_f32_16x16x32_bf16 v[36:39], v[162:165], v[198:201], v[36:39]
	v_mfma_f32_16x16x32_bf16 v[28:31], v[144:147], v[206:209], v[28:31]
	v_mfma_f32_16x16x32_bf16 v[20:23], v[162:165], v[206:209], v[20:23]
	v_mfma_f32_16x16x32_bf16 v[12:15], v[144:147], v[214:217], v[12:15]
	v_mfma_f32_16x16x32_bf16 v[4:7], v[162:165], v[214:217], v[4:7]
	v_mfma_f32_16x16x32_bf16 v[60:63], v[158:161], v[194:197], v[60:63]
	v_mfma_f32_16x16x32_bf16 v[52:55], v[166:169], v[194:197], v[52:55]
	v_mfma_f32_16x16x32_bf16 v[44:47], v[158:161], v[202:205], v[44:47]
	v_mfma_f32_16x16x32_bf16 v[36:39], v[166:169], v[202:205], v[36:39]
	v_mfma_f32_16x16x32_bf16 v[28:31], v[158:161], v[210:213], v[28:31]
	v_mfma_f32_16x16x32_bf16 v[20:23], v[166:169], v[210:213], v[20:23]
	v_mfma_f32_16x16x32_bf16 v[12:15], v[158:161], v[218:221], v[12:15]
	v_mfma_f32_16x16x32_bf16 v[4:7], v[166:169], v[218:221], v[4:7]
	s_setprio 0
	s_setprio 1
	v_mfma_f32_16x16x32_bf16 v[56:59], v[170:173], v[190:193], v[56:59]
	v_mfma_f32_16x16x32_bf16 v[48:51], v[178:181], v[190:193], v[48:51]
	v_mfma_f32_16x16x32_bf16 v[40:43], v[170:173], v[198:201], v[40:43]
	v_mfma_f32_16x16x32_bf16 v[32:35], v[178:181], v[198:201], v[32:35]
	v_mfma_f32_16x16x32_bf16 v[24:27], v[170:173], v[206:209], v[24:27]
	v_mfma_f32_16x16x32_bf16 v[16:19], v[178:181], v[206:209], v[16:19]
	v_mfma_f32_16x16x32_bf16 v[8:11], v[170:173], v[214:217], v[8:11]
	v_mfma_f32_16x16x32_bf16 v[0:3], v[178:181], v[214:217], v[0:3]
	v_mfma_f32_16x16x32_bf16 v[56:59], v[174:177], v[194:197], v[56:59]
	v_mfma_f32_16x16x32_bf16 v[48:51], v[184:187], v[194:197], v[48:51]
	v_mfma_f32_16x16x32_bf16 v[40:43], v[174:177], v[202:205], v[40:43]
	v_mfma_f32_16x16x32_bf16 v[32:35], v[184:187], v[202:205], v[32:35]
	v_mfma_f32_16x16x32_bf16 v[24:27], v[174:177], v[210:213], v[24:27]
	v_mfma_f32_16x16x32_bf16 v[16:19], v[184:187], v[210:213], v[16:19]
	v_mfma_f32_16x16x32_bf16 v[8:11], v[174:177], v[218:221], v[8:11]
	v_mfma_f32_16x16x32_bf16 v[0:3], v[184:187], v[218:221], v[0:3]
	s_setprio 0
	s_barrier
	s_add_i32 s47, 0, 0x18000
	v_add_u32_e32 v157, s47, v151
	s_add_i32 s48, 0, 0x1c000
	ds_read_b128 v[144:147], v157
	ds_read_b128 v[158:161], v157 offset:1024
	ds_read_b128 v[162:165], v157 offset:2048
	ds_read_b128 v[166:169], v157 offset:3072
	v_add_u32_e32 v157, s48, v151
	ds_read_b128 v[170:173], v157
	ds_read_b128 v[174:177], v157 offset:1024
	ds_read_b128 v[178:181], v157 offset:2048
	ds_read_b128 v[184:187], v157 offset:3072
	s_add_u32 s24, s24, 0x80000
	s_addc_u32 s25, s25, 0
	s_mov_b32 m0, s30
	v_lshl_add_u64 v[228:229], s[24:25], 0, v[128:129]
	ds_read_b128 v[190:193], v155 offset:32768
	ds_read_b128 v[194:197], v155 offset:33792
	ds_read_b128 v[198:201], v155 offset:34816
	ds_read_b128 v[202:205], v155 offset:35840
	ds_read_b128 v[206:209], v155 offset:36864
	ds_read_b128 v[210:213], v155 offset:37888
	ds_read_b128 v[214:217], v155 offset:38912
	ds_read_b128 v[218:221], v155 offset:39936
	global_load_lds_dwordx4 v[228:229], off
	v_lshl_add_u64 v[228:229], s[24:25], 0, v[132:133]
	s_mov_b32 m0, s31
	s_nop 0
	global_load_lds_dwordx4 v[228:229], off
	s_waitcnt vmcnt(8)
	s_waitcnt lgkmcnt(0)
	s_barrier
	s_setprio 1
	s_waitcnt lgkmcnt(0)
	v_mfma_f32_16x16x32_bf16 v[124:127], v[144:147], v[190:193], v[124:127]
	v_mfma_f32_16x16x32_bf16 v[116:119], v[162:165], v[190:193], v[116:119]
	v_mfma_f32_16x16x32_bf16 v[108:111], v[144:147], v[198:201], v[108:111]
	v_mfma_f32_16x16x32_bf16 v[100:103], v[162:165], v[198:201], v[100:103]
	v_mfma_f32_16x16x32_bf16 v[92:95], v[144:147], v[206:209], v[92:95]
	v_mfma_f32_16x16x32_bf16 v[84:87], v[162:165], v[206:209], v[84:87]
	v_mfma_f32_16x16x32_bf16 v[76:79], v[144:147], v[214:217], v[76:79]
	v_mfma_f32_16x16x32_bf16 v[68:71], v[162:165], v[214:217], v[68:71]
	v_mfma_f32_16x16x32_bf16 v[124:127], v[158:161], v[194:197], v[124:127]
	v_mfma_f32_16x16x32_bf16 v[116:119], v[166:169], v[194:197], v[116:119]
	v_mfma_f32_16x16x32_bf16 v[108:111], v[158:161], v[202:205], v[108:111]
	v_mfma_f32_16x16x32_bf16 v[100:103], v[166:169], v[202:205], v[100:103]
	v_mfma_f32_16x16x32_bf16 v[92:95], v[158:161], v[210:213], v[92:95]
	v_mfma_f32_16x16x32_bf16 v[84:87], v[166:169], v[210:213], v[84:87]
	v_mfma_f32_16x16x32_bf16 v[76:79], v[158:161], v[218:221], v[76:79]
	v_mfma_f32_16x16x32_bf16 v[68:71], v[166:169], v[218:221], v[68:71]
	s_setprio 0
	s_setprio 1
	v_mfma_f32_16x16x32_bf16 v[120:123], v[170:173], v[190:193], v[120:123]
	v_mfma_f32_16x16x32_bf16 v[112:115], v[178:181], v[190:193], v[112:115]
	v_mfma_f32_16x16x32_bf16 v[104:107], v[170:173], v[198:201], v[104:107]
	v_mfma_f32_16x16x32_bf16 v[96:99], v[178:181], v[198:201], v[96:99]
	v_mfma_f32_16x16x32_bf16 v[88:91], v[170:173], v[206:209], v[88:91]
	v_mfma_f32_16x16x32_bf16 v[80:83], v[178:181], v[206:209], v[80:83]
	v_mfma_f32_16x16x32_bf16 v[72:75], v[170:173], v[214:217], v[72:75]
	v_mfma_f32_16x16x32_bf16 v[64:67], v[178:181], v[214:217], v[64:67]
	v_mfma_f32_16x16x32_bf16 v[120:123], v[174:177], v[194:197], v[120:123]
	v_mfma_f32_16x16x32_bf16 v[112:115], v[184:187], v[194:197], v[112:115]
	v_mfma_f32_16x16x32_bf16 v[104:107], v[174:177], v[202:205], v[104:107]
	v_mfma_f32_16x16x32_bf16 v[96:99], v[184:187], v[202:205], v[96:99]
	v_mfma_f32_16x16x32_bf16 v[88:91], v[174:177], v[210:213], v[88:91]
	v_mfma_f32_16x16x32_bf16 v[80:83], v[184:187], v[210:213], v[80:83]
	v_mfma_f32_16x16x32_bf16 v[72:75], v[174:177], v[218:221], v[72:75]
	v_mfma_f32_16x16x32_bf16 v[64:67], v[184:187], v[218:221], v[64:67]
	s_setprio 0
	s_barrier
	s_add_i32 s24, s47, s27
	v_lshl_add_u64 v[148:149], v[148:149], 0, s[6:7]
	s_mov_b32 m0, s24
	ds_read_b128 v[190:193], v155 offset:49152
	ds_read_b128 v[194:197], v155 offset:50176
	ds_read_b128 v[198:201], v155 offset:51200
	ds_read_b128 v[202:205], v155 offset:52224
	ds_read_b128 v[206:209], v155 offset:53248
	ds_read_b128 v[210:213], v155 offset:54272
	ds_read_b128 v[214:217], v155 offset:55296
	ds_read_b128 v[218:221], v155 offset:56320
	global_load_lds_dwordx4 v[148:149], off
	s_add_i32 m0, s24, 0x2000
	s_add_u32 s22, s22, 0x80080
	v_lshl_add_u64 v[148:149], v[222:223], 0, s[6:7]
	s_addc_u32 s23, s23, 0
	s_add_i32 s24, s48, s27
	global_load_lds_dwordx4 v[148:149], off
	v_lshl_add_u64 v[148:149], s[22:23], 0, v[130:131]
	s_mov_b32 m0, s24
	s_nop 0
	global_load_lds_dwordx4 v[148:149], off
	v_lshl_add_u64 v[148:149], s[22:23], 0, v[134:135]
	s_add_i32 m0, s24, 0x2000
	s_nop 0
	global_load_lds_dwordx4 v[148:149], off
	v_lshl_add_u64 v[148:149], v[224:225], 0, s[6:7]
	s_mov_b32 m0, s34
	s_nop 0
	global_load_lds_dwordx4 v[148:149], off
	v_lshl_add_u64 v[148:149], v[226:227], 0, s[6:7]
	s_mov_b32 m0, s35
	s_nop 0
	global_load_lds_dwordx4 v[148:149], off
	s_waitcnt vmcnt(8)
	s_waitcnt lgkmcnt(0)
	s_barrier
	s_setprio 1
	s_waitcnt lgkmcnt(0)
	v_mfma_f32_16x16x32_bf16 v[60:63], v[144:147], v[190:193], v[60:63]
	v_mfma_f32_16x16x32_bf16 v[52:55], v[162:165], v[190:193], v[52:55]
	v_mfma_f32_16x16x32_bf16 v[44:47], v[144:147], v[198:201], v[44:47]
	v_mfma_f32_16x16x32_bf16 v[36:39], v[162:165], v[198:201], v[36:39]
	v_mfma_f32_16x16x32_bf16 v[28:31], v[144:147], v[206:209], v[28:31]
	v_mfma_f32_16x16x32_bf16 v[20:23], v[162:165], v[206:209], v[20:23]
	v_mfma_f32_16x16x32_bf16 v[12:15], v[144:147], v[214:217], v[12:15]
	v_mfma_f32_16x16x32_bf16 v[4:7], v[162:165], v[214:217], v[4:7]
	v_mfma_f32_16x16x32_bf16 v[60:63], v[158:161], v[194:197], v[60:63]
	v_mfma_f32_16x16x32_bf16 v[52:55], v[166:169], v[194:197], v[52:55]
	v_mfma_f32_16x16x32_bf16 v[44:47], v[158:161], v[202:205], v[44:47]
	v_mfma_f32_16x16x32_bf16 v[36:39], v[166:169], v[202:205], v[36:39]
	v_mfma_f32_16x16x32_bf16 v[28:31], v[158:161], v[210:213], v[28:31]
	v_mfma_f32_16x16x32_bf16 v[20:23], v[166:169], v[210:213], v[20:23]
	v_mfma_f32_16x16x32_bf16 v[12:15], v[158:161], v[218:221], v[12:15]
	v_mfma_f32_16x16x32_bf16 v[4:7], v[166:169], v[218:221], v[4:7]
	s_setprio 0
	s_setprio 1
	v_mfma_f32_16x16x32_bf16 v[56:59], v[170:173], v[190:193], v[56:59]
	v_mfma_f32_16x16x32_bf16 v[48:51], v[178:181], v[190:193], v[48:51]
	s_add_i32 s46, s46, 2
	s_add_u32 s20, s20, 0x100
	s_addc_u32 s21, s21, 0
	s_add_u32 s44, s44, 0x100
	s_addc_u32 s45, s45, 0
	s_cmp_gt_u32 s46, 29
	v_mfma_f32_16x16x32_bf16 v[40:43], v[170:173], v[198:201], v[40:43]
	v_mfma_f32_16x16x32_bf16 v[32:35], v[178:181], v[198:201], v[32:35]
	v_mfma_f32_16x16x32_bf16 v[24:27], v[170:173], v[206:209], v[24:27]
	v_mfma_f32_16x16x32_bf16 v[16:19], v[178:181], v[206:209], v[16:19]
	v_mfma_f32_16x16x32_bf16 v[8:11], v[170:173], v[214:217], v[8:11]
	v_mfma_f32_16x16x32_bf16 v[0:3], v[178:181], v[214:217], v[0:3]
	v_mfma_f32_16x16x32_bf16 v[56:59], v[174:177], v[194:197], v[56:59]
	v_mfma_f32_16x16x32_bf16 v[48:51], v[184:187], v[194:197], v[48:51]
	v_mfma_f32_16x16x32_bf16 v[40:43], v[174:177], v[202:205], v[40:43]
	v_mfma_f32_16x16x32_bf16 v[32:35], v[184:187], v[202:205], v[32:35]
	v_mfma_f32_16x16x32_bf16 v[24:27], v[174:177], v[210:213], v[24:27]
	v_mfma_f32_16x16x32_bf16 v[16:19], v[184:187], v[210:213], v[16:19]
	v_mfma_f32_16x16x32_bf16 v[8:11], v[174:177], v[218:221], v[8:11]
	v_mfma_f32_16x16x32_bf16 v[0:3], v[184:187], v[218:221], v[0:3]
	s_setprio 0
	s_barrier
	s_cbranch_scc0 .LBB0_504
	s_and_b64 vcc, exec, s[8:9]
	s_cbranch_vccz .LBB0_507
	s_barrier

.LBB0_1013:
	ds_read_b128 v[140:143], v149
	ds_read_b128 v[154:157], v149 offset:1024
	ds_read_b128 v[158:161], v149 offset:2048
	ds_read_b128 v[162:165], v149 offset:3072
	ds_read_b128 v[166:169], v150
	ds_read_b128 v[170:173], v150 offset:1024
	ds_read_b128 v[174:177], v150 offset:2048
	ds_read_b128 v[178:181], v150 offset:3072
	s_add_u32 s22, s20, 0x100
	s_addc_u32 s23, s21, 0
	s_cmpk_eq_i32 s48, 0x54
	s_cselect_b32 s27, s1, s23
	s_cselect_b32 s26, s0, s22
	s_cselect_b32 s25, s3, s47
	s_cselect_b32 s24, s2, s46
	v_lshl_add_u64 v[144:145], s[20:21], 0, v[132:133]
	s_add_i32 m0, s29, 0xc000
	ds_read_b128 v[184:187], v151
	ds_read_b128 v[190:193], v151 offset:1024
	ds_read_b128 v[194:197], v151 offset:2048
	ds_read_b128 v[198:201], v151 offset:3072
	ds_read_b128 v[202:205], v151 offset:4096
	ds_read_b128 v[206:209], v151 offset:5120
	ds_read_b128 v[210:213], v151 offset:6144
	ds_read_b128 v[214:217], v151 offset:7168
	global_load_lds_dwordx4 v[144:145], off
	v_lshl_add_u64 v[144:145], s[20:21], 0, v[134:135]
	s_add_i32 m0, s29, 0xe000
	s_nop 0
	global_load_lds_dwordx4 v[144:145], off
	s_waitcnt vmcnt(8)
	s_waitcnt lgkmcnt(0)
	s_barrier
	s_setprio 1
	s_waitcnt lgkmcnt(0)
	v_mfma_f32_16x16x32_bf16 v[124:127], v[140:143], v[184:187], v[124:127]
	v_mfma_f32_16x16x32_bf16 v[120:123], v[158:161], v[184:187], v[120:123]
	v_mfma_f32_16x16x32_bf16 v[108:111], v[140:143], v[194:197], v[108:111]
	v_mfma_f32_16x16x32_bf16 v[104:107], v[158:161], v[194:197], v[104:107]
	v_mfma_f32_16x16x32_bf16 v[92:95], v[140:143], v[202:205], v[92:95]
	v_mfma_f32_16x16x32_bf16 v[88:91], v[158:161], v[202:205], v[88:91]
	v_mfma_f32_16x16x32_bf16 v[76:79], v[140:143], v[210:213], v[76:79]
	v_mfma_f32_16x16x32_bf16 v[72:75], v[158:161], v[210:213], v[72:75]
	v_mfma_f32_16x16x32_bf16 v[124:127], v[154:157], v[190:193], v[124:127]
	v_mfma_f32_16x16x32_bf16 v[120:123], v[162:165], v[190:193], v[120:123]
	v_mfma_f32_16x16x32_bf16 v[108:111], v[154:157], v[198:201], v[108:111]
	v_mfma_f32_16x16x32_bf16 v[104:107], v[162:165], v[198:201], v[104:107]
	v_mfma_f32_16x16x32_bf16 v[92:95], v[154:157], v[206:209], v[92:95]
	v_mfma_f32_16x16x32_bf16 v[88:91], v[162:165], v[206:209], v[88:91]
	v_mfma_f32_16x16x32_bf16 v[76:79], v[154:157], v[214:217], v[76:79]
	v_mfma_f32_16x16x32_bf16 v[72:75], v[162:165], v[214:217], v[72:75]
	s_setprio 0
	s_setprio 1
	v_mfma_f32_16x16x32_bf16 v[116:119], v[166:169], v[184:187], v[116:119]
	v_mfma_f32_16x16x32_bf16 v[112:115], v[174:177], v[184:187], v[112:115]
	v_mfma_f32_16x16x32_bf16 v[100:103], v[166:169], v[194:197], v[100:103]
	v_mfma_f32_16x16x32_bf16 v[96:99], v[174:177], v[194:197], v[96:99]
	v_mfma_f32_16x16x32_bf16 v[84:87], v[166:169], v[202:205], v[84:87]
	v_mfma_f32_16x16x32_bf16 v[80:83], v[174:177], v[202:205], v[80:83]
	v_mfma_f32_16x16x32_bf16 v[68:71], v[166:169], v[210:213], v[68:71]
	v_mfma_f32_16x16x32_bf16 v[64:67], v[174:177], v[210:213], v[64:67]
	v_mfma_f32_16x16x32_bf16 v[116:119], v[170:173], v[190:193], v[116:119]
	v_mfma_f32_16x16x32_bf16 v[112:115], v[178:181], v[190:193], v[112:115]
	v_mfma_f32_16x16x32_bf16 v[100:103], v[170:173], v[198:201], v[100:103]
	v_mfma_f32_16x16x32_bf16 v[96:99], v[178:181], v[198:201], v[96:99]
	v_mfma_f32_16x16x32_bf16 v[84:87], v[170:173], v[206:209], v[84:87]
	v_mfma_f32_16x16x32_bf16 v[80:83], v[178:181], v[206:209], v[80:83]
	v_mfma_f32_16x16x32_bf16 v[68:71], v[170:173], v[214:217], v[68:71]
	v_mfma_f32_16x16x32_bf16 v[64:67], v[178:181], v[214:217], v[64:67]
	s_setprio 0
	s_barrier
	s_add_i32 s20, s40, s28
	v_lshl_add_u64 v[144:145], s[24:25], 0, v[128:129]
	s_mov_b32 m0, s20
	ds_read_b128 v[184:187], v151 offset:16384
	ds_read_b128 v[190:193], v151 offset:17408
	ds_read_b128 v[194:197], v151 offset:18432
	ds_read_b128 v[198:201], v151 offset:19456
	ds_read_b128 v[202:205], v151 offset:20480
	ds_read_b128 v[206:209], v151 offset:21504
	ds_read_b128 v[210:213], v151 offset:22528
	ds_read_b128 v[214:217], v151 offset:23552
	global_load_lds_dwordx4 v[144:145], off
	s_add_i32 m0, s20, 0x2000
	s_add_u32 s20, s24, 0x160000
	v_lshl_add_u64 v[218:219], s[24:25], 0, v[130:131]
	s_addc_u32 s21, s25, 0
	s_add_i32 s49, s41, s28
	global_load_lds_dwordx4 v[218:219], off
	v_lshl_add_u64 v[220:221], s[20:21], 0, v[128:129]
	s_mov_b32 m0, s49
	v_lshl_add_u64 v[222:223], s[26:27], 0, v[130:131]
	global_load_lds_dwordx4 v[220:221], off
	v_lshl_add_u64 v[220:221], s[20:21], 0, v[130:131]
	s_add_i32 m0, s49, 0x2000
	s_nop 0
	global_load_lds_dwordx4 v[220:221], off
	v_lshl_add_u64 v[220:221], s[26:27], 0, v[128:129]
	s_mov_b32 m0, s29
	s_nop 0
	global_load_lds_dwordx4 v[220:221], off
	s_mov_b32 m0, s30
	s_nop 0
	global_load_lds_dwordx4 v[222:223], off
	s_waitcnt vmcnt(8)
	s_waitcnt lgkmcnt(0)
	s_barrier
	s_setprio 1
	s_waitcnt lgkmcnt(0)
	v_mfma_f32_16x16x32_bf16 v[60:63], v[140:143], v[184:187], v[60:63]
	v_mfma_f32_16x16x32_bf16 v[56:59], v[158:161], v[184:187], v[56:59]
	v_mfma_f32_16x16x32_bf16 v[44:47], v[140:143], v[194:197], v[44:47]
	v_mfma_f32_16x16x32_bf16 v[40:43], v[158:161], v[194:197], v[40:43]
	v_mfma_f32_16x16x32_bf16 v[28:31], v[140:143], v[202:205], v[28:31]
	v_mfma_f32_16x16x32_bf16 v[24:27], v[158:161], v[202:205], v[24:27]
	v_mfma_f32_16x16x32_bf16 v[12:15], v[140:143], v[210:213], v[12:15]
	v_mfma_f32_16x16x32_bf16 v[8:11], v[158:161], v[210:213], v[8:11]
	v_mfma_f32_16x16x32_bf16 v[60:63], v[154:157], v[190:193], v[60:63]
	v_mfma_f32_16x16x32_bf16 v[56:59], v[162:165], v[190:193], v[56:59]
	v_mfma_f32_16x16x32_bf16 v[44:47], v[154:157], v[198:201], v[44:47]
	v_mfma_f32_16x16x32_bf16 v[40:43], v[162:165], v[198:201], v[40:43]
	v_mfma_f32_16x16x32_bf16 v[28:31], v[154:157], v[206:209], v[28:31]
	v_mfma_f32_16x16x32_bf16 v[24:27], v[162:165], v[206:209], v[24:27]
	v_mfma_f32_16x16x32_bf16 v[12:15], v[154:157], v[214:217], v[12:15]
	v_mfma_f32_16x16x32_bf16 v[8:11], v[162:165], v[214:217], v[8:11]
	s_setprio 0
	s_setprio 1
	v_mfma_f32_16x16x32_bf16 v[52:55], v[166:169], v[184:187], v[52:55]
	v_mfma_f32_16x16x32_bf16 v[48:51], v[174:177], v[184:187], v[48:51]
	v_mfma_f32_16x16x32_bf16 v[36:39], v[166:169], v[194:197], v[36:39]
	v_mfma_f32_16x16x32_bf16 v[32:35], v[174:177], v[194:197], v[32:35]
	v_mfma_f32_16x16x32_bf16 v[20:23], v[166:169], v[202:205], v[20:23]
	v_mfma_f32_16x16x32_bf16 v[16:19], v[174:177], v[202:205], v[16:19]
	v_mfma_f32_16x16x32_bf16 v[4:7], v[166:169], v[210:213], v[4:7]
	v_mfma_f32_16x16x32_bf16 v[0:3], v[174:177], v[210:213], v[0:3]
	v_mfma_f32_16x16x32_bf16 v[52:55], v[170:173], v[190:193], v[52:55]
	v_mfma_f32_16x16x32_bf16 v[48:51], v[178:181], v[190:193], v[48:51]
	v_mfma_f32_16x16x32_bf16 v[36:39], v[170:173], v[198:201], v[36:39]
	v_mfma_f32_16x16x32_bf16 v[32:35], v[178:181], v[198:201], v[32:35]
	v_mfma_f32_16x16x32_bf16 v[20:23], v[170:173], v[206:209], v[20:23]
	v_mfma_f32_16x16x32_bf16 v[16:19], v[178:181], v[206:209], v[16:19]
	v_mfma_f32_16x16x32_bf16 v[4:7], v[170:173], v[214:217], v[4:7]
	v_mfma_f32_16x16x32_bf16 v[0:3], v[178:181], v[214:217], v[0:3]
	s_setprio 0
	s_barrier
	s_add_i32 s49, 0, 0x18000
	v_add_u32_e32 v153, s49, v147
	s_add_i32 s50, 0, 0x1c000
	ds_read_b128 v[140:143], v153
	ds_read_b128 v[154:157], v153 offset:1024
	ds_read_b128 v[158:161], v153 offset:2048
	ds_read_b128 v[162:165], v153 offset:3072
	v_add_u32_e32 v153, s50, v147
	ds_read_b128 v[166:169], v153
	ds_read_b128 v[170:173], v153 offset:1024
	ds_read_b128 v[174:177], v153 offset:2048
	ds_read_b128 v[178:181], v153 offset:3072
	s_add_u32 s20, s26, 0x160000
	s_addc_u32 s21, s27, 0
	s_mov_b32 m0, s31
	v_lshl_add_u64 v[224:225], s[20:21], 0, v[128:129]
	ds_read_b128 v[184:187], v151 offset:32768
	ds_read_b128 v[190:193], v151 offset:33792
	ds_read_b128 v[194:197], v151 offset:34816
	ds_read_b128 v[198:201], v151 offset:35840
	ds_read_b128 v[202:205], v151 offset:36864
	ds_read_b128 v[206:209], v151 offset:37888
	ds_read_b128 v[210:213], v151 offset:38912
	ds_read_b128 v[214:217], v151 offset:39936
	global_load_lds_dwordx4 v[224:225], off
	v_lshl_add_u64 v[224:225], s[20:21], 0, v[130:131]
	s_mov_b32 m0, s33
	s_nop 0
	global_load_lds_dwordx4 v[224:225], off
	s_waitcnt vmcnt(8)
	s_waitcnt lgkmcnt(0)
	s_barrier
	s_setprio 1
	s_waitcnt lgkmcnt(0)
	v_mfma_f32_16x16x32_bf16 v[124:127], v[140:143], v[184:187], v[124:127]
	v_mfma_f32_16x16x32_bf16 v[120:123], v[158:161], v[184:187], v[120:123]
	v_mfma_f32_16x16x32_bf16 v[108:111], v[140:143], v[194:197], v[108:111]
	v_mfma_f32_16x16x32_bf16 v[104:107], v[158:161], v[194:197], v[104:107]
	v_mfma_f32_16x16x32_bf16 v[92:95], v[140:143], v[202:205], v[92:95]
	v_mfma_f32_16x16x32_bf16 v[88:91], v[158:161], v[202:205], v[88:91]
	v_mfma_f32_16x16x32_bf16 v[76:79], v[140:143], v[210:213], v[76:79]
	v_mfma_f32_16x16x32_bf16 v[72:75], v[158:161], v[210:213], v[72:75]
	v_mfma_f32_16x16x32_bf16 v[124:127], v[154:157], v[190:193], v[124:127]
	v_mfma_f32_16x16x32_bf16 v[120:123], v[162:165], v[190:193], v[120:123]
	v_mfma_f32_16x16x32_bf16 v[108:111], v[154:157], v[198:201], v[108:111]
	v_mfma_f32_16x16x32_bf16 v[104:107], v[162:165], v[198:201], v[104:107]
	v_mfma_f32_16x16x32_bf16 v[92:95], v[154:157], v[206:209], v[92:95]
	v_mfma_f32_16x16x32_bf16 v[88:91], v[162:165], v[206:209], v[88:91]
	v_mfma_f32_16x16x32_bf16 v[76:79], v[154:157], v[214:217], v[76:79]
	v_mfma_f32_16x16x32_bf16 v[72:75], v[162:165], v[214:217], v[72:75]
	s_setprio 0
	s_setprio 1
	v_mfma_f32_16x16x32_bf16 v[116:119], v[166:169], v[184:187], v[116:119]
	v_mfma_f32_16x16x32_bf16 v[112:115], v[174:177], v[184:187], v[112:115]
	v_mfma_f32_16x16x32_bf16 v[100:103], v[166:169], v[194:197], v[100:103]
	v_mfma_f32_16x16x32_bf16 v[96:99], v[174:177], v[194:197], v[96:99]
	v_mfma_f32_16x16x32_bf16 v[84:87], v[166:169], v[202:205], v[84:87]
	v_mfma_f32_16x16x32_bf16 v[80:83], v[174:177], v[202:205], v[80:83]
	v_mfma_f32_16x16x32_bf16 v[68:71], v[166:169], v[210:213], v[68:71]
	v_mfma_f32_16x16x32_bf16 v[64:67], v[174:177], v[210:213], v[64:67]
	v_mfma_f32_16x16x32_bf16 v[116:119], v[170:173], v[190:193], v[116:119]
	v_mfma_f32_16x16x32_bf16 v[112:115], v[178:181], v[190:193], v[112:115]
	v_mfma_f32_16x16x32_bf16 v[100:103], v[170:173], v[198:201], v[100:103]
	v_mfma_f32_16x16x32_bf16 v[96:99], v[178:181], v[198:201], v[96:99]
	v_mfma_f32_16x16x32_bf16 v[84:87], v[170:173], v[206:209], v[84:87]
	v_mfma_f32_16x16x32_bf16 v[80:83], v[178:181], v[206:209], v[80:83]
	v_mfma_f32_16x16x32_bf16 v[68:71], v[170:173], v[214:217], v[68:71]
	v_mfma_f32_16x16x32_bf16 v[64:67], v[178:181], v[214:217], v[64:67]
	s_setprio 0
	s_barrier
	s_add_i32 s20, s49, s28
	v_lshl_add_u64 v[144:145], v[144:145], 0, s[12:13]
	s_mov_b32 m0, s20
	ds_read_b128 v[184:187], v151 offset:49152
	ds_read_b128 v[190:193], v151 offset:50176
	ds_read_b128 v[194:197], v151 offset:51200
	ds_read_b128 v[198:201], v151 offset:52224
	ds_read_b128 v[202:205], v151 offset:53248
	ds_read_b128 v[206:209], v151 offset:54272
	ds_read_b128 v[210:213], v151 offset:55296
	ds_read_b128 v[214:217], v151 offset:56320
	global_load_lds_dwordx4 v[144:145], off
	s_add_i32 m0, s20, 0x2000
	s_add_u32 s20, s24, 0x160080
	v_lshl_add_u64 v[144:145], v[218:219], 0, s[12:13]
	s_addc_u32 s21, s25, 0
	s_add_i32 s24, s50, s28
	global_load_lds_dwordx4 v[144:145], off
	v_lshl_add_u64 v[144:145], s[20:21], 0, v[128:129]
	s_mov_b32 m0, s24
	s_nop 0
	global_load_lds_dwordx4 v[144:145], off
	v_lshl_add_u64 v[144:145], s[20:21], 0, v[130:131]
	s_add_i32 m0, s24, 0x2000
	s_nop 0
	global_load_lds_dwordx4 v[144:145], off
	v_lshl_add_u64 v[144:145], v[220:221], 0, s[12:13]
	s_mov_b32 m0, s35
	s_nop 0
	global_load_lds_dwordx4 v[144:145], off
	v_lshl_add_u64 v[144:145], v[222:223], 0, s[12:13]
	s_mov_b32 m0, s36
	s_nop 0
	global_load_lds_dwordx4 v[144:145], off
	s_waitcnt vmcnt(8)
	s_waitcnt lgkmcnt(0)
	s_barrier
	s_setprio 1
	s_waitcnt lgkmcnt(0)
	v_mfma_f32_16x16x32_bf16 v[60:63], v[140:143], v[184:187], v[60:63]
	v_mfma_f32_16x16x32_bf16 v[56:59], v[158:161], v[184:187], v[56:59]
	v_mfma_f32_16x16x32_bf16 v[44:47], v[140:143], v[194:197], v[44:47]
	v_mfma_f32_16x16x32_bf16 v[40:43], v[158:161], v[194:197], v[40:43]
	v_mfma_f32_16x16x32_bf16 v[28:31], v[140:143], v[202:205], v[28:31]
	v_mfma_f32_16x16x32_bf16 v[24:27], v[158:161], v[202:205], v[24:27]
	v_mfma_f32_16x16x32_bf16 v[12:15], v[140:143], v[210:213], v[12:15]
	v_mfma_f32_16x16x32_bf16 v[8:11], v[158:161], v[210:213], v[8:11]
	v_mfma_f32_16x16x32_bf16 v[60:63], v[154:157], v[190:193], v[60:63]
	v_mfma_f32_16x16x32_bf16 v[56:59], v[162:165], v[190:193], v[56:59]
	v_mfma_f32_16x16x32_bf16 v[44:47], v[154:157], v[198:201], v[44:47]
	v_mfma_f32_16x16x32_bf16 v[40:43], v[162:165], v[198:201], v[40:43]
	v_mfma_f32_16x16x32_bf16 v[28:31], v[154:157], v[206:209], v[28:31]
	v_mfma_f32_16x16x32_bf16 v[24:27], v[162:165], v[206:209], v[24:27]
	v_mfma_f32_16x16x32_bf16 v[12:15], v[154:157], v[214:217], v[12:15]
	v_mfma_f32_16x16x32_bf16 v[8:11], v[162:165], v[214:217], v[8:11]
	s_setprio 0
	s_setprio 1
	v_mfma_f32_16x16x32_bf16 v[52:55], v[166:169], v[184:187], v[52:55]
	v_mfma_f32_16x16x32_bf16 v[48:51], v[174:177], v[184:187], v[48:51]
	s_add_i32 s48, s48, 2
	s_add_u32 s46, s46, 0x100
	s_addc_u32 s47, s47, 0
	s_cmpk_gt_u32 s48, 0x55
	s_mov_b64 s[20:21], s[22:23]
	v_mfma_f32_16x16x32_bf16 v[36:39], v[166:169], v[194:197], v[36:39]
	v_mfma_f32_16x16x32_bf16 v[32:35], v[174:177], v[194:197], v[32:35]
	v_mfma_f32_16x16x32_bf16 v[20:23], v[166:169], v[202:205], v[20:23]
	v_mfma_f32_16x16x32_bf16 v[16:19], v[174:177], v[202:205], v[16:19]
	v_mfma_f32_16x16x32_bf16 v[4:7], v[166:169], v[210:213], v[4:7]
	v_mfma_f32_16x16x32_bf16 v[0:3], v[174:177], v[210:213], v[0:3]
	v_mfma_f32_16x16x32_bf16 v[52:55], v[170:173], v[190:193], v[52:55]
	v_mfma_f32_16x16x32_bf16 v[48:51], v[178:181], v[190:193], v[48:51]
	v_mfma_f32_16x16x32_bf16 v[36:39], v[170:173], v[198:201], v[36:39]
	v_mfma_f32_16x16x32_bf16 v[32:35], v[178:181], v[198:201], v[32:35]
	v_mfma_f32_16x16x32_bf16 v[20:23], v[170:173], v[206:209], v[20:23]
	v_mfma_f32_16x16x32_bf16 v[16:19], v[178:181], v[206:209], v[16:19]
	v_mfma_f32_16x16x32_bf16 v[4:7], v[170:173], v[214:217], v[4:7]
	v_mfma_f32_16x16x32_bf16 v[0:3], v[178:181], v[214:217], v[0:3]
	s_setprio 0
	s_barrier
	s_cbranch_scc0 .LBB0_1013
	s_and_b64 vcc, exec, s[18:19]
	s_cbranch_vccz .LBB0_1016
	s_barrier

.LBB0_1114:
	ds_read_b128 v[146:149], v156
	ds_read_b128 v[160:163], v156 offset:1024
	ds_read_b128 v[164:167], v156 offset:2048
	ds_read_b128 v[168:171], v156 offset:3072
	ds_read_b128 v[172:175], v157
	ds_read_b128 v[176:179], v157 offset:1024
	ds_read_b128 v[184:187], v157 offset:2048
	ds_read_b128 v[190:193], v157 offset:3072
	s_add_u32 s36, s8, 0xfff80080
	s_addc_u32 s37, s9, -1
	s_cmp_eq_u32 s58, 28
	s_cselect_b32 s39, s1, s37
	s_cselect_b32 s38, s7, s36
	s_cselect_b32 s37, s27, s57
	s_cselect_b32 s36, s29, s56
	v_lshl_add_u64 v[150:151], s[8:9], 0, v[138:139]
	s_add_i32 m0, s40, 0xc000
	ds_read_b128 v[194:197], v158
	ds_read_b128 v[198:201], v158 offset:1024
	ds_read_b128 v[202:205], v158 offset:2048
	ds_read_b128 v[206:209], v158 offset:3072
	ds_read_b128 v[210:213], v158 offset:4096
	ds_read_b128 v[214:217], v158 offset:5120
	ds_read_b128 v[218:221], v158 offset:6144
	ds_read_b128 v[222:225], v158 offset:7168
	global_load_lds_dwordx4 v[150:151], off
	v_lshl_add_u64 v[150:151], s[8:9], 0, v[140:141]
	s_add_i32 m0, s40, 0xe000
	s_nop 0
	global_load_lds_dwordx4 v[150:151], off
	s_waitcnt vmcnt(8)
	s_waitcnt lgkmcnt(0)
	s_barrier
	s_setprio 1
	s_waitcnt lgkmcnt(0)
	v_mfma_f32_16x16x32_bf16 v[124:127], v[146:149], v[194:197], v[124:127]
	v_mfma_f32_16x16x32_bf16 v[120:123], v[164:167], v[194:197], v[120:123]
	v_mfma_f32_16x16x32_bf16 v[108:111], v[146:149], v[202:205], v[108:111]
	v_mfma_f32_16x16x32_bf16 v[104:107], v[164:167], v[202:205], v[104:107]
	v_mfma_f32_16x16x32_bf16 v[92:95], v[146:149], v[210:213], v[92:95]
	v_mfma_f32_16x16x32_bf16 v[88:91], v[164:167], v[210:213], v[88:91]
	v_mfma_f32_16x16x32_bf16 v[76:79], v[146:149], v[218:221], v[76:79]
	v_mfma_f32_16x16x32_bf16 v[72:75], v[164:167], v[218:221], v[72:75]
	v_mfma_f32_16x16x32_bf16 v[124:127], v[160:163], v[198:201], v[124:127]
	v_mfma_f32_16x16x32_bf16 v[120:123], v[168:171], v[198:201], v[120:123]
	v_mfma_f32_16x16x32_bf16 v[108:111], v[160:163], v[206:209], v[108:111]
	v_mfma_f32_16x16x32_bf16 v[104:107], v[168:171], v[206:209], v[104:107]
	v_mfma_f32_16x16x32_bf16 v[92:95], v[160:163], v[214:217], v[92:95]
	v_mfma_f32_16x16x32_bf16 v[88:91], v[168:171], v[214:217], v[88:91]
	v_mfma_f32_16x16x32_bf16 v[76:79], v[160:163], v[222:225], v[76:79]
	v_mfma_f32_16x16x32_bf16 v[72:75], v[168:171], v[222:225], v[72:75]
	s_setprio 0
	s_setprio 1
	v_mfma_f32_16x16x32_bf16 v[116:119], v[172:175], v[194:197], v[116:119]
	v_mfma_f32_16x16x32_bf16 v[112:115], v[184:187], v[194:197], v[112:115]
	v_mfma_f32_16x16x32_bf16 v[100:103], v[172:175], v[202:205], v[100:103]
	v_mfma_f32_16x16x32_bf16 v[96:99], v[184:187], v[202:205], v[96:99]
	v_mfma_f32_16x16x32_bf16 v[84:87], v[172:175], v[210:213], v[84:87]
	v_mfma_f32_16x16x32_bf16 v[80:83], v[184:187], v[210:213], v[80:83]
	v_mfma_f32_16x16x32_bf16 v[68:71], v[172:175], v[218:221], v[68:71]
	v_mfma_f32_16x16x32_bf16 v[64:67], v[184:187], v[218:221], v[64:67]
	v_mfma_f32_16x16x32_bf16 v[116:119], v[176:179], v[198:201], v[116:119]
	v_mfma_f32_16x16x32_bf16 v[112:115], v[190:193], v[198:201], v[112:115]
	v_mfma_f32_16x16x32_bf16 v[100:103], v[176:179], v[206:209], v[100:103]
	v_mfma_f32_16x16x32_bf16 v[96:99], v[190:193], v[206:209], v[96:99]
	v_mfma_f32_16x16x32_bf16 v[84:87], v[176:179], v[214:217], v[84:87]
	v_mfma_f32_16x16x32_bf16 v[80:83], v[190:193], v[214:217], v[80:83]
	v_mfma_f32_16x16x32_bf16 v[68:71], v[176:179], v[222:225], v[68:71]
	v_mfma_f32_16x16x32_bf16 v[64:67], v[190:193], v[222:225], v[64:67]
	s_setprio 0
	s_barrier
	s_add_i32 s59, s50, s33
	v_lshl_add_u64 v[150:151], s[36:37], 0, v[130:131]
	s_mov_b32 m0, s59
	ds_read_b128 v[194:197], v158 offset:16384
	ds_read_b128 v[198:201], v158 offset:17408
	ds_read_b128 v[202:205], v158 offset:18432
	ds_read_b128 v[206:209], v158 offset:19456
	ds_read_b128 v[210:213], v158 offset:20480
	ds_read_b128 v[214:217], v158 offset:21504
	ds_read_b128 v[218:221], v158 offset:22528
	ds_read_b128 v[222:225], v158 offset:23552
	global_load_lds_dwordx4 v[150:151], off
	s_add_i32 m0, s59, 0x2000
	s_add_u32 s60, s36, 0x80000
	v_lshl_add_u64 v[180:181], s[36:37], 0, v[134:135]
	s_addc_u32 s61, s37, 0
	s_add_i32 s59, s51, s33
	global_load_lds_dwordx4 v[180:181], off
	v_lshl_add_u64 v[226:227], s[60:61], 0, v[130:131]
	s_mov_b32 m0, s59
	v_lshl_add_u64 v[228:229], s[38:39], 0, v[132:133]
	global_load_lds_dwordx4 v[226:227], off
	v_lshl_add_u64 v[226:227], s[60:61], 0, v[134:135]
	s_add_i32 m0, s59, 0x2000
	s_nop 0
	global_load_lds_dwordx4 v[226:227], off
	v_lshl_add_u64 v[226:227], s[38:39], 0, v[128:129]
	s_mov_b32 m0, s40
	s_nop 0
	global_load_lds_dwordx4 v[226:227], off
	s_mov_b32 m0, s41
	s_nop 0
	global_load_lds_dwordx4 v[228:229], off
	s_waitcnt vmcnt(8)
	s_waitcnt lgkmcnt(0)
	s_barrier
	s_setprio 1
	s_waitcnt lgkmcnt(0)
	v_mfma_f32_16x16x32_bf16 v[60:63], v[146:149], v[194:197], v[60:63]
	v_mfma_f32_16x16x32_bf16 v[56:59], v[164:167], v[194:197], v[56:59]
	v_mfma_f32_16x16x32_bf16 v[44:47], v[146:149], v[202:205], v[44:47]
	v_mfma_f32_16x16x32_bf16 v[40:43], v[164:167], v[202:205], v[40:43]
	v_mfma_f32_16x16x32_bf16 v[28:31], v[146:149], v[210:213], v[28:31]
	v_mfma_f32_16x16x32_bf16 v[24:27], v[164:167], v[210:213], v[24:27]
	v_mfma_f32_16x16x32_bf16 v[12:15], v[146:149], v[218:221], v[12:15]
	v_mfma_f32_16x16x32_bf16 v[8:11], v[164:167], v[218:221], v[8:11]
	v_mfma_f32_16x16x32_bf16 v[60:63], v[160:163], v[198:201], v[60:63]
	v_mfma_f32_16x16x32_bf16 v[56:59], v[168:171], v[198:201], v[56:59]
	v_mfma_f32_16x16x32_bf16 v[44:47], v[160:163], v[206:209], v[44:47]
	v_mfma_f32_16x16x32_bf16 v[40:43], v[168:171], v[206:209], v[40:43]
	v_mfma_f32_16x16x32_bf16 v[28:31], v[160:163], v[214:217], v[28:31]
	v_mfma_f32_16x16x32_bf16 v[24:27], v[168:171], v[214:217], v[24:27]
	v_mfma_f32_16x16x32_bf16 v[12:15], v[160:163], v[222:225], v[12:15]
	v_mfma_f32_16x16x32_bf16 v[8:11], v[168:171], v[222:225], v[8:11]
	s_setprio 0
	s_setprio 1
	v_mfma_f32_16x16x32_bf16 v[52:55], v[172:175], v[194:197], v[52:55]
	v_mfma_f32_16x16x32_bf16 v[48:51], v[184:187], v[194:197], v[48:51]
	v_mfma_f32_16x16x32_bf16 v[36:39], v[172:175], v[202:205], v[36:39]
	v_mfma_f32_16x16x32_bf16 v[32:35], v[184:187], v[202:205], v[32:35]
	v_mfma_f32_16x16x32_bf16 v[20:23], v[172:175], v[210:213], v[20:23]
	v_mfma_f32_16x16x32_bf16 v[16:19], v[184:187], v[210:213], v[16:19]
	v_mfma_f32_16x16x32_bf16 v[4:7], v[172:175], v[218:221], v[4:7]
	v_mfma_f32_16x16x32_bf16 v[0:3], v[184:187], v[218:221], v[0:3]
	v_mfma_f32_16x16x32_bf16 v[52:55], v[176:179], v[198:201], v[52:55]
	v_mfma_f32_16x16x32_bf16 v[48:51], v[190:193], v[198:201], v[48:51]
	v_mfma_f32_16x16x32_bf16 v[36:39], v[176:179], v[206:209], v[36:39]
	v_mfma_f32_16x16x32_bf16 v[32:35], v[190:193], v[206:209], v[32:35]
	v_mfma_f32_16x16x32_bf16 v[20:23], v[176:179], v[214:217], v[20:23]
	v_mfma_f32_16x16x32_bf16 v[16:19], v[190:193], v[214:217], v[16:19]
	v_mfma_f32_16x16x32_bf16 v[4:7], v[176:179], v[222:225], v[4:7]
	v_mfma_f32_16x16x32_bf16 v[0:3], v[190:193], v[222:225], v[0:3]
	s_setprio 0
	s_barrier
	s_add_i32 s59, 0, 0x18000
	v_add_u32_e32 v152, s59, v154
	s_add_i32 s60, 0, 0x1c000
	ds_read_b128 v[146:149], v152
	ds_read_b128 v[160:163], v152 offset:1024
	ds_read_b128 v[164:167], v152 offset:2048
	ds_read_b128 v[168:171], v152 offset:3072
	v_add_u32_e32 v152, s60, v154
	ds_read_b128 v[172:175], v152
	ds_read_b128 v[176:179], v152 offset:1024
	ds_read_b128 v[184:187], v152 offset:2048
	ds_read_b128 v[190:193], v152 offset:3072
	s_add_u32 s38, s38, 0x80000
	s_addc_u32 s39, s39, 0
	s_mov_b32 m0, s42
	v_lshl_add_u64 v[230:231], s[38:39], 0, v[128:129]
	ds_read_b128 v[194:197], v158 offset:32768
	ds_read_b128 v[198:201], v158 offset:33792
	ds_read_b128 v[202:205], v158 offset:34816
	ds_read_b128 v[206:209], v158 offset:35840
	ds_read_b128 v[210:213], v158 offset:36864
	ds_read_b128 v[214:217], v158 offset:37888
	ds_read_b128 v[218:221], v158 offset:38912
	ds_read_b128 v[222:225], v158 offset:39936
	global_load_lds_dwordx4 v[230:231], off
	v_lshl_add_u64 v[230:231], s[38:39], 0, v[132:133]
	s_mov_b32 m0, s43
	s_nop 0
	global_load_lds_dwordx4 v[230:231], off
	s_waitcnt vmcnt(8)
	s_waitcnt lgkmcnt(0)
	s_barrier
	s_setprio 1
	s_waitcnt lgkmcnt(0)
	v_mfma_f32_16x16x32_bf16 v[124:127], v[146:149], v[194:197], v[124:127]
	v_mfma_f32_16x16x32_bf16 v[120:123], v[164:167], v[194:197], v[120:123]
	v_mfma_f32_16x16x32_bf16 v[108:111], v[146:149], v[202:205], v[108:111]
	v_mfma_f32_16x16x32_bf16 v[104:107], v[164:167], v[202:205], v[104:107]
	v_mfma_f32_16x16x32_bf16 v[92:95], v[146:149], v[210:213], v[92:95]
	v_mfma_f32_16x16x32_bf16 v[88:91], v[164:167], v[210:213], v[88:91]
	v_mfma_f32_16x16x32_bf16 v[76:79], v[146:149], v[218:221], v[76:79]
	v_mfma_f32_16x16x32_bf16 v[72:75], v[164:167], v[218:221], v[72:75]
	v_mfma_f32_16x16x32_bf16 v[124:127], v[160:163], v[198:201], v[124:127]
	v_mfma_f32_16x16x32_bf16 v[120:123], v[168:171], v[198:201], v[120:123]
	v_mfma_f32_16x16x32_bf16 v[108:111], v[160:163], v[206:209], v[108:111]
	v_mfma_f32_16x16x32_bf16 v[104:107], v[168:171], v[206:209], v[104:107]
	v_mfma_f32_16x16x32_bf16 v[92:95], v[160:163], v[214:217], v[92:95]
	v_mfma_f32_16x16x32_bf16 v[88:91], v[168:171], v[214:217], v[88:91]
	v_mfma_f32_16x16x32_bf16 v[76:79], v[160:163], v[222:225], v[76:79]
	v_mfma_f32_16x16x32_bf16 v[72:75], v[168:171], v[222:225], v[72:75]
	s_setprio 0
	s_setprio 1
	v_mfma_f32_16x16x32_bf16 v[116:119], v[172:175], v[194:197], v[116:119]
	v_mfma_f32_16x16x32_bf16 v[112:115], v[184:187], v[194:197], v[112:115]
	v_mfma_f32_16x16x32_bf16 v[100:103], v[172:175], v[202:205], v[100:103]
	v_mfma_f32_16x16x32_bf16 v[96:99], v[184:187], v[202:205], v[96:99]
	v_mfma_f32_16x16x32_bf16 v[84:87], v[172:175], v[210:213], v[84:87]
	v_mfma_f32_16x16x32_bf16 v[80:83], v[184:187], v[210:213], v[80:83]
	v_mfma_f32_16x16x32_bf16 v[68:71], v[172:175], v[218:221], v[68:71]
	v_mfma_f32_16x16x32_bf16 v[64:67], v[184:187], v[218:221], v[64:67]
	v_mfma_f32_16x16x32_bf16 v[116:119], v[176:179], v[198:201], v[116:119]
	v_mfma_f32_16x16x32_bf16 v[112:115], v[190:193], v[198:201], v[112:115]
	v_mfma_f32_16x16x32_bf16 v[100:103], v[176:179], v[206:209], v[100:103]
	v_mfma_f32_16x16x32_bf16 v[96:99], v[190:193], v[206:209], v[96:99]
	v_mfma_f32_16x16x32_bf16 v[84:87], v[176:179], v[214:217], v[84:87]
	v_mfma_f32_16x16x32_bf16 v[80:83], v[190:193], v[214:217], v[80:83]
	v_mfma_f32_16x16x32_bf16 v[68:71], v[176:179], v[222:225], v[68:71]
	v_mfma_f32_16x16x32_bf16 v[64:67], v[190:193], v[222:225], v[64:67]
	s_setprio 0
	s_barrier
	s_add_i32 s38, s59, s33
	v_lshl_add_u64 v[150:151], v[150:151], 0, s[20:21]
	s_mov_b32 m0, s38
	ds_read_b128 v[194:197], v158 offset:49152
	ds_read_b128 v[198:201], v158 offset:50176
	ds_read_b128 v[202:205], v158 offset:51200
	ds_read_b128 v[206:209], v158 offset:52224
	ds_read_b128 v[210:213], v158 offset:53248
	ds_read_b128 v[214:217], v158 offset:54272
	ds_read_b128 v[218:221], v158 offset:55296
	ds_read_b128 v[222:225], v158 offset:56320
	global_load_lds_dwordx4 v[150:151], off
	s_add_i32 m0, s38, 0x2000
	s_add_u32 s36, s36, 0x80080
	v_lshl_add_u64 v[150:151], v[180:181], 0, s[20:21]
	s_addc_u32 s37, s37, 0
	s_add_i32 s38, s60, s33
	global_load_lds_dwordx4 v[150:151], off
	v_lshl_add_u64 v[150:151], s[36:37], 0, v[130:131]
	s_mov_b32 m0, s38
	s_nop 0
	global_load_lds_dwordx4 v[150:151], off
	v_lshl_add_u64 v[150:151], s[36:37], 0, v[134:135]
	s_add_i32 m0, s38, 0x2000
	s_nop 0
	global_load_lds_dwordx4 v[150:151], off
	v_lshl_add_u64 v[150:151], v[226:227], 0, s[20:21]
	s_mov_b32 m0, s45
	s_nop 0
	global_load_lds_dwordx4 v[150:151], off
	v_lshl_add_u64 v[150:151], v[228:229], 0, s[20:21]
	s_mov_b32 m0, s46
	s_nop 0
	global_load_lds_dwordx4 v[150:151], off
	s_waitcnt vmcnt(8)
	s_waitcnt lgkmcnt(0)
	s_barrier
	s_setprio 1
	s_waitcnt lgkmcnt(0)
	v_mfma_f32_16x16x32_bf16 v[60:63], v[146:149], v[194:197], v[60:63]
	v_mfma_f32_16x16x32_bf16 v[56:59], v[164:167], v[194:197], v[56:59]
	v_mfma_f32_16x16x32_bf16 v[44:47], v[146:149], v[202:205], v[44:47]
	v_mfma_f32_16x16x32_bf16 v[40:43], v[164:167], v[202:205], v[40:43]
	v_mfma_f32_16x16x32_bf16 v[28:31], v[146:149], v[210:213], v[28:31]
	v_mfma_f32_16x16x32_bf16 v[24:27], v[164:167], v[210:213], v[24:27]
	v_mfma_f32_16x16x32_bf16 v[12:15], v[146:149], v[218:221], v[12:15]
	v_mfma_f32_16x16x32_bf16 v[8:11], v[164:167], v[218:221], v[8:11]
	v_mfma_f32_16x16x32_bf16 v[60:63], v[160:163], v[198:201], v[60:63]
	v_mfma_f32_16x16x32_bf16 v[56:59], v[168:171], v[198:201], v[56:59]
	v_mfma_f32_16x16x32_bf16 v[44:47], v[160:163], v[206:209], v[44:47]
	v_mfma_f32_16x16x32_bf16 v[40:43], v[168:171], v[206:209], v[40:43]
	v_mfma_f32_16x16x32_bf16 v[28:31], v[160:163], v[214:217], v[28:31]
	v_mfma_f32_16x16x32_bf16 v[24:27], v[168:171], v[214:217], v[24:27]
	v_mfma_f32_16x16x32_bf16 v[12:15], v[160:163], v[222:225], v[12:15]
	v_mfma_f32_16x16x32_bf16 v[8:11], v[168:171], v[222:225], v[8:11]
	s_setprio 0
	s_setprio 1
	v_mfma_f32_16x16x32_bf16 v[52:55], v[172:175], v[194:197], v[52:55]
	v_mfma_f32_16x16x32_bf16 v[48:51], v[184:187], v[194:197], v[48:51]
	s_add_i32 s58, s58, 2
	s_add_u32 s8, s8, 0x100
	s_addc_u32 s9, s9, 0
	s_add_u32 s56, s56, 0x100
	s_addc_u32 s57, s57, 0
	s_cmp_gt_u32 s58, 29
	v_mfma_f32_16x16x32_bf16 v[36:39], v[172:175], v[202:205], v[36:39]
	v_mfma_f32_16x16x32_bf16 v[32:35], v[184:187], v[202:205], v[32:35]
	v_mfma_f32_16x16x32_bf16 v[20:23], v[172:175], v[210:213], v[20:23]
	v_mfma_f32_16x16x32_bf16 v[16:19], v[184:187], v[210:213], v[16:19]
	v_mfma_f32_16x16x32_bf16 v[4:7], v[172:175], v[218:221], v[4:7]
	v_mfma_f32_16x16x32_bf16 v[0:3], v[184:187], v[218:221], v[0:3]
	v_mfma_f32_16x16x32_bf16 v[52:55], v[176:179], v[198:201], v[52:55]
	v_mfma_f32_16x16x32_bf16 v[48:51], v[190:193], v[198:201], v[48:51]
	v_mfma_f32_16x16x32_bf16 v[36:39], v[176:179], v[206:209], v[36:39]
	v_mfma_f32_16x16x32_bf16 v[32:35], v[190:193], v[206:209], v[32:35]
	v_mfma_f32_16x16x32_bf16 v[20:23], v[176:179], v[214:217], v[20:23]
	v_mfma_f32_16x16x32_bf16 v[16:19], v[190:193], v[214:217], v[16:19]
	v_mfma_f32_16x16x32_bf16 v[4:7], v[176:179], v[222:225], v[4:7]
	v_mfma_f32_16x16x32_bf16 v[0:3], v[190:193], v[222:225], v[0:3]
	s_setprio 0
	s_barrier
	s_cbranch_scc0 .LBB0_1114
	s_and_b64 vcc, exec, s[22:23]
	s_cbranch_vccz .LBB0_1117
	s_barrier

.LBB0_2212:
	ds_read_b128 v[140:143], v147
	ds_read_b128 v[154:157], v147 offset:1024
	ds_read_b128 v[158:161], v147 offset:2048
	ds_read_b128 v[162:165], v147 offset:3072
	ds_read_b128 v[166:169], v152
	ds_read_b128 v[170:173], v152 offset:1024
	ds_read_b128 v[174:177], v152 offset:2048
	ds_read_b128 v[178:181], v152 offset:3072
	s_add_u32 s30, s28, 0x100
	s_addc_u32 s31, s29, 0
	s_cmp_eq_u32 s52, 28
	s_cselect_b32 s37, s19, s31
	s_cselect_b32 s36, s25, s30
	s_cselect_b32 s35, s17, s51
	s_cselect_b32 s34, s49, s50
	v_lshl_add_u64 v[216:217], s[28:29], 0, v[132:133]
	s_add_i32 m0, s27, 0xc000
	ds_read_b128 v[184:187], v153
	ds_read_b128 v[188:191], v153 offset:1024
	ds_read_b128 v[192:195], v153 offset:2048
	ds_read_b128 v[196:199], v153 offset:3072
	ds_read_b128 v[200:203], v153 offset:4096
	ds_read_b128 v[204:207], v153 offset:5120
	ds_read_b128 v[208:211], v153 offset:6144
	ds_read_b128 v[212:215], v153 offset:7168
	global_load_lds_dwordx4 v[216:217], off
	v_lshl_add_u64 v[216:217], s[28:29], 0, v[134:135]
	s_add_i32 m0, s27, 0xe000
	s_nop 0
	global_load_lds_dwordx4 v[216:217], off
	s_waitcnt vmcnt(8)
	s_waitcnt lgkmcnt(0)
	s_barrier
	s_setprio 1
	s_waitcnt lgkmcnt(0)
	v_mfma_f32_16x16x32_bf16 v[124:127], v[140:143], v[184:187], v[124:127]
	v_mfma_f32_16x16x32_bf16 v[120:123], v[158:161], v[184:187], v[120:123]
	v_mfma_f32_16x16x32_bf16 v[108:111], v[140:143], v[192:195], v[108:111]
	v_mfma_f32_16x16x32_bf16 v[104:107], v[158:161], v[192:195], v[104:107]
	v_mfma_f32_16x16x32_bf16 v[92:95], v[140:143], v[200:203], v[92:95]
	v_mfma_f32_16x16x32_bf16 v[88:91], v[158:161], v[200:203], v[88:91]
	v_mfma_f32_16x16x32_bf16 v[76:79], v[140:143], v[208:211], v[76:79]
	v_mfma_f32_16x16x32_bf16 v[72:75], v[158:161], v[208:211], v[72:75]
	v_mfma_f32_16x16x32_bf16 v[124:127], v[154:157], v[188:191], v[124:127]
	v_mfma_f32_16x16x32_bf16 v[120:123], v[162:165], v[188:191], v[120:123]
	v_mfma_f32_16x16x32_bf16 v[108:111], v[154:157], v[196:199], v[108:111]
	v_mfma_f32_16x16x32_bf16 v[104:107], v[162:165], v[196:199], v[104:107]
	v_mfma_f32_16x16x32_bf16 v[92:95], v[154:157], v[204:207], v[92:95]
	v_mfma_f32_16x16x32_bf16 v[88:91], v[162:165], v[204:207], v[88:91]
	v_mfma_f32_16x16x32_bf16 v[76:79], v[154:157], v[212:215], v[76:79]
	v_mfma_f32_16x16x32_bf16 v[72:75], v[162:165], v[212:215], v[72:75]
	s_setprio 0
	s_setprio 1
	v_mfma_f32_16x16x32_bf16 v[116:119], v[166:169], v[184:187], v[116:119]
	v_mfma_f32_16x16x32_bf16 v[112:115], v[174:177], v[184:187], v[112:115]
	v_mfma_f32_16x16x32_bf16 v[100:103], v[166:169], v[192:195], v[100:103]
	v_mfma_f32_16x16x32_bf16 v[96:99], v[174:177], v[192:195], v[96:99]
	v_mfma_f32_16x16x32_bf16 v[84:87], v[166:169], v[200:203], v[84:87]
	v_mfma_f32_16x16x32_bf16 v[80:83], v[174:177], v[200:203], v[80:83]
	v_mfma_f32_16x16x32_bf16 v[68:71], v[166:169], v[208:211], v[68:71]
	v_mfma_f32_16x16x32_bf16 v[64:67], v[174:177], v[208:211], v[64:67]
	v_mfma_f32_16x16x32_bf16 v[116:119], v[170:173], v[188:191], v[116:119]
	v_mfma_f32_16x16x32_bf16 v[112:115], v[178:181], v[188:191], v[112:115]
	v_mfma_f32_16x16x32_bf16 v[100:103], v[170:173], v[196:199], v[100:103]
	v_mfma_f32_16x16x32_bf16 v[96:99], v[178:181], v[196:199], v[96:99]
	v_mfma_f32_16x16x32_bf16 v[84:87], v[170:173], v[204:207], v[84:87]
	v_mfma_f32_16x16x32_bf16 v[80:83], v[178:181], v[204:207], v[80:83]
	v_mfma_f32_16x16x32_bf16 v[68:71], v[170:173], v[212:215], v[68:71]
	v_mfma_f32_16x16x32_bf16 v[64:67], v[178:181], v[212:215], v[64:67]
	s_setprio 0
	s_barrier
	s_add_i32 s28, s47, s33
	v_lshl_add_u64 v[216:217], s[34:35], 0, v[128:129]
	s_mov_b32 m0, s28
	ds_read_b128 v[184:187], v153 offset:16384
	ds_read_b128 v[188:191], v153 offset:17408
	ds_read_b128 v[192:195], v153 offset:18432
	ds_read_b128 v[196:199], v153 offset:19456
	ds_read_b128 v[200:203], v153 offset:20480
	ds_read_b128 v[204:207], v153 offset:21504
	ds_read_b128 v[208:211], v153 offset:22528
	ds_read_b128 v[212:215], v153 offset:23552
	global_load_lds_dwordx4 v[216:217], off
	s_add_i32 m0, s28, 0x2000
	s_add_u32 s28, s34, 0x80000
	v_lshl_add_u64 v[218:219], s[34:35], 0, v[130:131]
	s_addc_u32 s29, s35, 0
	s_add_i32 s53, s48, s33
	global_load_lds_dwordx4 v[218:219], off
	v_lshl_add_u64 v[220:221], s[28:29], 0, v[128:129]
	s_mov_b32 m0, s53
	v_lshl_add_u64 v[222:223], s[36:37], 0, v[130:131]
	global_load_lds_dwordx4 v[220:221], off
	v_lshl_add_u64 v[220:221], s[28:29], 0, v[130:131]
	s_add_i32 m0, s53, 0x2000
	s_nop 0
	global_load_lds_dwordx4 v[220:221], off
	v_lshl_add_u64 v[220:221], s[36:37], 0, v[128:129]
	s_mov_b32 m0, s27
	s_nop 0
	global_load_lds_dwordx4 v[220:221], off
	s_mov_b32 m0, s38
	s_nop 0
	global_load_lds_dwordx4 v[222:223], off
	s_waitcnt vmcnt(8)
	s_waitcnt lgkmcnt(0)
	s_barrier
	s_setprio 1
	s_waitcnt lgkmcnt(0)
	v_mfma_f32_16x16x32_bf16 v[60:63], v[140:143], v[184:187], v[60:63]
	v_mfma_f32_16x16x32_bf16 v[56:59], v[158:161], v[184:187], v[56:59]
	v_mfma_f32_16x16x32_bf16 v[44:47], v[140:143], v[192:195], v[44:47]
	v_mfma_f32_16x16x32_bf16 v[40:43], v[158:161], v[192:195], v[40:43]
	v_mfma_f32_16x16x32_bf16 v[28:31], v[140:143], v[200:203], v[28:31]
	v_mfma_f32_16x16x32_bf16 v[24:27], v[158:161], v[200:203], v[24:27]
	v_mfma_f32_16x16x32_bf16 v[12:15], v[140:143], v[208:211], v[12:15]
	v_mfma_f32_16x16x32_bf16 v[8:11], v[158:161], v[208:211], v[8:11]
	v_mfma_f32_16x16x32_bf16 v[60:63], v[154:157], v[188:191], v[60:63]
	v_mfma_f32_16x16x32_bf16 v[56:59], v[162:165], v[188:191], v[56:59]
	v_mfma_f32_16x16x32_bf16 v[44:47], v[154:157], v[196:199], v[44:47]
	v_mfma_f32_16x16x32_bf16 v[40:43], v[162:165], v[196:199], v[40:43]
	v_mfma_f32_16x16x32_bf16 v[28:31], v[154:157], v[204:207], v[28:31]
	v_mfma_f32_16x16x32_bf16 v[24:27], v[162:165], v[204:207], v[24:27]
	v_mfma_f32_16x16x32_bf16 v[12:15], v[154:157], v[212:215], v[12:15]
	v_mfma_f32_16x16x32_bf16 v[8:11], v[162:165], v[212:215], v[8:11]
	s_setprio 0
	s_setprio 1
	v_mfma_f32_16x16x32_bf16 v[52:55], v[166:169], v[184:187], v[52:55]
	v_mfma_f32_16x16x32_bf16 v[48:51], v[174:177], v[184:187], v[48:51]
	v_mfma_f32_16x16x32_bf16 v[36:39], v[166:169], v[192:195], v[36:39]
	v_mfma_f32_16x16x32_bf16 v[32:35], v[174:177], v[192:195], v[32:35]
	v_mfma_f32_16x16x32_bf16 v[20:23], v[166:169], v[200:203], v[20:23]
	v_mfma_f32_16x16x32_bf16 v[16:19], v[174:177], v[200:203], v[16:19]
	v_mfma_f32_16x16x32_bf16 v[4:7], v[166:169], v[208:211], v[4:7]
	v_mfma_f32_16x16x32_bf16 v[0:3], v[174:177], v[208:211], v[0:3]
	v_mfma_f32_16x16x32_bf16 v[52:55], v[170:173], v[188:191], v[52:55]
	v_mfma_f32_16x16x32_bf16 v[48:51], v[178:181], v[188:191], v[48:51]
	v_mfma_f32_16x16x32_bf16 v[36:39], v[170:173], v[196:199], v[36:39]
	v_mfma_f32_16x16x32_bf16 v[32:35], v[178:181], v[196:199], v[32:35]
	v_mfma_f32_16x16x32_bf16 v[20:23], v[170:173], v[204:207], v[20:23]
	v_mfma_f32_16x16x32_bf16 v[16:19], v[178:181], v[204:207], v[16:19]
	v_mfma_f32_16x16x32_bf16 v[4:7], v[170:173], v[212:215], v[4:7]
	v_mfma_f32_16x16x32_bf16 v[0:3], v[178:181], v[212:215], v[0:3]
	s_setprio 0
	s_barrier
	s_add_i32 s53, 0, 0x18000
	s_add_i32 s54, 0, 0x1c000
	v_add_u32_e32 v162, s53, v145
	v_add_u32_e32 v178, s54, v145
	ds_read_b128 v[140:143], v162
	ds_read_b128 v[154:157], v162 offset:1024
	ds_read_b128 v[158:161], v162 offset:2048
	ds_read_b128 v[162:165], v162 offset:3072
	ds_read_b128 v[166:169], v178
	ds_read_b128 v[170:173], v178 offset:1024
	ds_read_b128 v[174:177], v178 offset:2048
	ds_read_b128 v[178:181], v178 offset:3072
	s_add_u32 s28, s36, 0x80000
	s_addc_u32 s29, s37, 0
	s_mov_b32 m0, s39
	v_lshl_add_u64 v[224:225], s[28:29], 0, v[128:129]
	ds_read_b128 v[184:187], v153 offset:32768
	ds_read_b128 v[188:191], v153 offset:33792
	ds_read_b128 v[192:195], v153 offset:34816
	ds_read_b128 v[196:199], v153 offset:35840
	ds_read_b128 v[200:203], v153 offset:36864
	ds_read_b128 v[204:207], v153 offset:37888
	ds_read_b128 v[208:211], v153 offset:38912
	ds_read_b128 v[212:215], v153 offset:39936
	global_load_lds_dwordx4 v[224:225], off
	v_lshl_add_u64 v[224:225], s[28:29], 0, v[130:131]
	s_mov_b32 m0, s40
	s_nop 0
	global_load_lds_dwordx4 v[224:225], off
	s_waitcnt vmcnt(8)
	s_waitcnt lgkmcnt(0)
	s_barrier
	s_setprio 1
	s_waitcnt lgkmcnt(0)
	v_mfma_f32_16x16x32_bf16 v[124:127], v[140:143], v[184:187], v[124:127]
	v_mfma_f32_16x16x32_bf16 v[120:123], v[158:161], v[184:187], v[120:123]
	v_mfma_f32_16x16x32_bf16 v[108:111], v[140:143], v[192:195], v[108:111]
	v_mfma_f32_16x16x32_bf16 v[104:107], v[158:161], v[192:195], v[104:107]
	v_mfma_f32_16x16x32_bf16 v[92:95], v[140:143], v[200:203], v[92:95]
	v_mfma_f32_16x16x32_bf16 v[88:91], v[158:161], v[200:203], v[88:91]
	v_mfma_f32_16x16x32_bf16 v[76:79], v[140:143], v[208:211], v[76:79]
	v_mfma_f32_16x16x32_bf16 v[72:75], v[158:161], v[208:211], v[72:75]
	v_mfma_f32_16x16x32_bf16 v[124:127], v[154:157], v[188:191], v[124:127]
	v_mfma_f32_16x16x32_bf16 v[120:123], v[162:165], v[188:191], v[120:123]
	v_mfma_f32_16x16x32_bf16 v[108:111], v[154:157], v[196:199], v[108:111]
	v_mfma_f32_16x16x32_bf16 v[104:107], v[162:165], v[196:199], v[104:107]
	v_mfma_f32_16x16x32_bf16 v[92:95], v[154:157], v[204:207], v[92:95]
	v_mfma_f32_16x16x32_bf16 v[88:91], v[162:165], v[204:207], v[88:91]
	v_mfma_f32_16x16x32_bf16 v[76:79], v[154:157], v[212:215], v[76:79]
	v_mfma_f32_16x16x32_bf16 v[72:75], v[162:165], v[212:215], v[72:75]
	s_setprio 0
	s_setprio 1
	v_mfma_f32_16x16x32_bf16 v[116:119], v[166:169], v[184:187], v[116:119]
	v_mfma_f32_16x16x32_bf16 v[112:115], v[174:177], v[184:187], v[112:115]
	v_mfma_f32_16x16x32_bf16 v[100:103], v[166:169], v[192:195], v[100:103]
	v_mfma_f32_16x16x32_bf16 v[96:99], v[174:177], v[192:195], v[96:99]
	v_mfma_f32_16x16x32_bf16 v[84:87], v[166:169], v[200:203], v[84:87]
	v_mfma_f32_16x16x32_bf16 v[80:83], v[174:177], v[200:203], v[80:83]
	v_mfma_f32_16x16x32_bf16 v[68:71], v[166:169], v[208:211], v[68:71]
	v_mfma_f32_16x16x32_bf16 v[64:67], v[174:177], v[208:211], v[64:67]
	v_mfma_f32_16x16x32_bf16 v[116:119], v[170:173], v[188:191], v[116:119]
	v_mfma_f32_16x16x32_bf16 v[112:115], v[178:181], v[188:191], v[112:115]
	v_mfma_f32_16x16x32_bf16 v[100:103], v[170:173], v[196:199], v[100:103]
	v_mfma_f32_16x16x32_bf16 v[96:99], v[178:181], v[196:199], v[96:99]
	v_mfma_f32_16x16x32_bf16 v[84:87], v[170:173], v[204:207], v[84:87]
	v_mfma_f32_16x16x32_bf16 v[80:83], v[178:181], v[204:207], v[80:83]
	v_mfma_f32_16x16x32_bf16 v[68:71], v[170:173], v[212:215], v[68:71]
	v_mfma_f32_16x16x32_bf16 v[64:67], v[178:181], v[212:215], v[64:67]
	s_setprio 0
	s_barrier
	s_add_i32 s28, s53, s33
	v_lshl_add_u64 v[216:217], v[216:217], 0, s[12:13]
	s_mov_b32 m0, s28
	ds_read_b128 v[184:187], v153 offset:49152
	ds_read_b128 v[188:191], v153 offset:50176
	ds_read_b128 v[192:195], v153 offset:51200
	ds_read_b128 v[196:199], v153 offset:52224
	ds_read_b128 v[200:203], v153 offset:53248
	ds_read_b128 v[204:207], v153 offset:54272
	ds_read_b128 v[208:211], v153 offset:55296
	ds_read_b128 v[212:215], v153 offset:56320
	global_load_lds_dwordx4 v[216:217], off
	s_add_i32 m0, s28, 0x2000
	s_add_u32 s28, s34, 0x80080
	v_lshl_add_u64 v[216:217], v[218:219], 0, s[12:13]
	s_addc_u32 s29, s35, 0
	s_add_i32 s34, s54, s33
	global_load_lds_dwordx4 v[216:217], off
	v_lshl_add_u64 v[216:217], s[28:29], 0, v[128:129]
	s_mov_b32 m0, s34
	s_nop 0
	global_load_lds_dwordx4 v[216:217], off
	v_lshl_add_u64 v[216:217], s[28:29], 0, v[130:131]
	s_add_i32 m0, s34, 0x2000
	s_nop 0
	global_load_lds_dwordx4 v[216:217], off
	v_lshl_add_u64 v[216:217], v[220:221], 0, s[12:13]
	s_mov_b32 m0, s42
	s_nop 0
	global_load_lds_dwordx4 v[216:217], off
	v_lshl_add_u64 v[216:217], v[222:223], 0, s[12:13]
	s_mov_b32 m0, s43
	s_nop 0
	global_load_lds_dwordx4 v[216:217], off
	s_waitcnt vmcnt(8)
	s_waitcnt lgkmcnt(0)
	s_barrier
	s_setprio 1
	s_waitcnt lgkmcnt(0)
	v_mfma_f32_16x16x32_bf16 v[60:63], v[140:143], v[184:187], v[60:63]
	v_mfma_f32_16x16x32_bf16 v[56:59], v[158:161], v[184:187], v[56:59]
	v_mfma_f32_16x16x32_bf16 v[44:47], v[140:143], v[192:195], v[44:47]
	v_mfma_f32_16x16x32_bf16 v[40:43], v[158:161], v[192:195], v[40:43]
	v_mfma_f32_16x16x32_bf16 v[28:31], v[140:143], v[200:203], v[28:31]
	v_mfma_f32_16x16x32_bf16 v[24:27], v[158:161], v[200:203], v[24:27]
	v_mfma_f32_16x16x32_bf16 v[12:15], v[140:143], v[208:211], v[12:15]
	v_mfma_f32_16x16x32_bf16 v[8:11], v[158:161], v[208:211], v[8:11]
	v_mfma_f32_16x16x32_bf16 v[60:63], v[154:157], v[188:191], v[60:63]
	v_mfma_f32_16x16x32_bf16 v[56:59], v[162:165], v[188:191], v[56:59]
	v_mfma_f32_16x16x32_bf16 v[44:47], v[154:157], v[196:199], v[44:47]
	v_mfma_f32_16x16x32_bf16 v[40:43], v[162:165], v[196:199], v[40:43]
	v_mfma_f32_16x16x32_bf16 v[28:31], v[154:157], v[204:207], v[28:31]
	v_mfma_f32_16x16x32_bf16 v[24:27], v[162:165], v[204:207], v[24:27]
	v_mfma_f32_16x16x32_bf16 v[12:15], v[154:157], v[212:215], v[12:15]
	v_mfma_f32_16x16x32_bf16 v[8:11], v[162:165], v[212:215], v[8:11]
	s_setprio 0
	s_setprio 1
	v_mfma_f32_16x16x32_bf16 v[52:55], v[166:169], v[184:187], v[52:55]
	v_mfma_f32_16x16x32_bf16 v[48:51], v[174:177], v[184:187], v[48:51]
	s_add_i32 s52, s52, 2
	s_add_u32 s50, s50, 0x100
	s_addc_u32 s51, s51, 0
	s_cmp_gt_u32 s52, 29
	s_mov_b64 s[28:29], s[30:31]
	v_mfma_f32_16x16x32_bf16 v[36:39], v[166:169], v[192:195], v[36:39]
	v_mfma_f32_16x16x32_bf16 v[32:35], v[174:177], v[192:195], v[32:35]
	v_mfma_f32_16x16x32_bf16 v[20:23], v[166:169], v[200:203], v[20:23]
	v_mfma_f32_16x16x32_bf16 v[16:19], v[174:177], v[200:203], v[16:19]
	v_mfma_f32_16x16x32_bf16 v[4:7], v[166:169], v[208:211], v[4:7]
	v_mfma_f32_16x16x32_bf16 v[0:3], v[174:177], v[208:211], v[0:3]
	v_mfma_f32_16x16x32_bf16 v[52:55], v[170:173], v[188:191], v[52:55]
	v_mfma_f32_16x16x32_bf16 v[48:51], v[178:181], v[188:191], v[48:51]
	v_mfma_f32_16x16x32_bf16 v[36:39], v[170:173], v[196:199], v[36:39]
	v_mfma_f32_16x16x32_bf16 v[32:35], v[178:181], v[196:199], v[32:35]
	v_mfma_f32_16x16x32_bf16 v[20:23], v[170:173], v[204:207], v[20:23]
	v_mfma_f32_16x16x32_bf16 v[16:19], v[178:181], v[204:207], v[16:19]
	v_mfma_f32_16x16x32_bf16 v[4:7], v[170:173], v[212:215], v[4:7]
	v_mfma_f32_16x16x32_bf16 v[0:3], v[178:181], v[212:215], v[0:3]
	s_setprio 0
	s_barrier
	s_cbranch_scc0 .LBB0_2212
	s_and_b64 vcc, exec, s[14:15]
	s_cbranch_vccz .LBB0_2215
	s_barrier

.LBB0_2311:
	ds_read_b128 v[144:147], v155
	ds_read_b128 v[160:163], v155 offset:1024
	ds_read_b128 v[164:167], v155 offset:2048
	ds_read_b128 v[168:171], v155 offset:3072
	ds_read_b128 v[172:175], v156
	ds_read_b128 v[176:179], v156 offset:1024
	ds_read_b128 v[184:187], v156 offset:2048
	ds_read_b128 v[188:191], v156 offset:3072
	s_add_u32 s22, s20, 0xfff80080
	s_addc_u32 s23, s21, -1
	s_cmp_eq_u32 s48, 28
	s_cselect_b32 s25, s15, s23
	s_cselect_b32 s24, s44, s22
	s_cselect_b32 s23, s13, s47
	s_cselect_b32 s22, s45, s46
	v_lshl_add_u64 v[180:181], s[20:21], 0, v[136:137]
	s_add_i32 m0, s30, 0xc000
	ds_read_b128 v[192:195], v157
	ds_read_b128 v[196:199], v157 offset:1024
	ds_read_b128 v[200:203], v157 offset:2048
	ds_read_b128 v[204:207], v157 offset:3072
	ds_read_b128 v[208:211], v157 offset:4096
	ds_read_b128 v[212:215], v157 offset:5120
	ds_read_b128 v[216:219], v157 offset:6144
	ds_read_b128 v[220:223], v157 offset:7168
	global_load_lds_dwordx4 v[180:181], off
	v_lshl_add_u64 v[180:181], s[20:21], 0, v[138:139]
	s_add_i32 m0, s30, 0xe000
	s_nop 0
	global_load_lds_dwordx4 v[180:181], off
	s_waitcnt vmcnt(8)
	s_waitcnt lgkmcnt(0)
	s_barrier
	s_setprio 1
	s_waitcnt lgkmcnt(0)
	v_mfma_f32_16x16x32_bf16 v[116:119], v[144:147], v[192:195], v[116:119]
	v_mfma_f32_16x16x32_bf16 v[112:115], v[164:167], v[192:195], v[112:115]
	v_mfma_f32_16x16x32_bf16 v[100:103], v[144:147], v[200:203], v[100:103]
	v_mfma_f32_16x16x32_bf16 v[96:99], v[164:167], v[200:203], v[96:99]
	v_mfma_f32_16x16x32_bf16 v[84:87], v[144:147], v[208:211], v[84:87]
	v_mfma_f32_16x16x32_bf16 v[80:83], v[164:167], v[208:211], v[80:83]
	v_mfma_f32_16x16x32_bf16 v[72:75], v[144:147], v[216:219], v[72:75]
	v_mfma_f32_16x16x32_bf16 v[64:67], v[164:167], v[216:219], v[64:67]
	v_mfma_f32_16x16x32_bf16 v[116:119], v[160:163], v[196:199], v[116:119]
	v_mfma_f32_16x16x32_bf16 v[112:115], v[168:171], v[196:199], v[112:115]
	v_mfma_f32_16x16x32_bf16 v[100:103], v[160:163], v[204:207], v[100:103]
	v_mfma_f32_16x16x32_bf16 v[96:99], v[168:171], v[204:207], v[96:99]
	v_mfma_f32_16x16x32_bf16 v[84:87], v[160:163], v[212:215], v[84:87]
	v_mfma_f32_16x16x32_bf16 v[80:83], v[168:171], v[212:215], v[80:83]
	v_mfma_f32_16x16x32_bf16 v[72:75], v[160:163], v[220:223], v[72:75]
	v_mfma_f32_16x16x32_bf16 v[64:67], v[168:171], v[220:223], v[64:67]
	s_setprio 0
	s_setprio 1
	v_mfma_f32_16x16x32_bf16 v[124:127], v[172:175], v[192:195], v[124:127]
	v_mfma_f32_16x16x32_bf16 v[120:123], v[184:187], v[192:195], v[120:123]
	v_mfma_f32_16x16x32_bf16 v[108:111], v[172:175], v[200:203], v[108:111]
	v_mfma_f32_16x16x32_bf16 v[104:107], v[184:187], v[200:203], v[104:107]
	v_mfma_f32_16x16x32_bf16 v[92:95], v[172:175], v[208:211], v[92:95]
	v_mfma_f32_16x16x32_bf16 v[88:91], v[184:187], v[208:211], v[88:91]
	v_mfma_f32_16x16x32_bf16 v[76:79], v[172:175], v[216:219], v[76:79]
	v_mfma_f32_16x16x32_bf16 v[68:71], v[184:187], v[216:219], v[68:71]
	v_mfma_f32_16x16x32_bf16 v[124:127], v[176:179], v[196:199], v[124:127]
	v_mfma_f32_16x16x32_bf16 v[120:123], v[188:191], v[196:199], v[120:123]
	v_mfma_f32_16x16x32_bf16 v[108:111], v[176:179], v[204:207], v[108:111]
	v_mfma_f32_16x16x32_bf16 v[104:107], v[188:191], v[204:207], v[104:107]
	v_mfma_f32_16x16x32_bf16 v[92:95], v[176:179], v[212:215], v[92:95]
	v_mfma_f32_16x16x32_bf16 v[88:91], v[188:191], v[212:215], v[88:91]
	v_mfma_f32_16x16x32_bf16 v[76:79], v[176:179], v[220:223], v[76:79]
	v_mfma_f32_16x16x32_bf16 v[68:71], v[188:191], v[220:223], v[68:71]
	s_setprio 0
	s_barrier
	s_add_i32 s49, s40, s29
	v_lshl_add_u64 v[180:181], s[22:23], 0, v[130:131]
	s_mov_b32 m0, s49
	ds_read_b128 v[192:195], v157 offset:16384
	ds_read_b128 v[196:199], v157 offset:17408
	ds_read_b128 v[200:203], v157 offset:18432
	ds_read_b128 v[204:207], v157 offset:19456
	ds_read_b128 v[208:211], v157 offset:20480
	ds_read_b128 v[212:215], v157 offset:21504
	ds_read_b128 v[216:219], v157 offset:22528
	ds_read_b128 v[220:223], v157 offset:23552
	global_load_lds_dwordx4 v[180:181], off
	s_add_i32 m0, s49, 0x2000
	s_add_u32 s50, s22, 0x80000
	v_lshl_add_u64 v[224:225], s[22:23], 0, v[134:135]
	s_addc_u32 s51, s23, 0
	s_add_i32 s49, s41, s29
	global_load_lds_dwordx4 v[224:225], off
	v_lshl_add_u64 v[226:227], s[50:51], 0, v[130:131]
	s_mov_b32 m0, s49
	v_lshl_add_u64 v[228:229], s[24:25], 0, v[132:133]
	global_load_lds_dwordx4 v[226:227], off
	v_lshl_add_u64 v[226:227], s[50:51], 0, v[134:135]
	s_add_i32 m0, s49, 0x2000
	s_nop 0
	global_load_lds_dwordx4 v[226:227], off
	v_lshl_add_u64 v[226:227], s[24:25], 0, v[128:129]
	s_mov_b32 m0, s30
	s_nop 0
	global_load_lds_dwordx4 v[226:227], off
	s_mov_b32 m0, s31
	s_nop 0
	global_load_lds_dwordx4 v[228:229], off
	s_waitcnt vmcnt(8)
	s_waitcnt lgkmcnt(0)
	s_barrier
	s_setprio 1
	s_waitcnt lgkmcnt(0)
	v_mfma_f32_16x16x32_bf16 v[52:55], v[144:147], v[192:195], v[52:55]
	v_mfma_f32_16x16x32_bf16 v[48:51], v[164:167], v[192:195], v[48:51]
	v_mfma_f32_16x16x32_bf16 v[36:39], v[144:147], v[200:203], v[36:39]
	v_mfma_f32_16x16x32_bf16 v[32:35], v[164:167], v[200:203], v[32:35]
	v_mfma_f32_16x16x32_bf16 v[20:23], v[144:147], v[208:211], v[20:23]
	v_mfma_f32_16x16x32_bf16 v[16:19], v[164:167], v[208:211], v[16:19]
	v_mfma_f32_16x16x32_bf16 v[4:7], v[144:147], v[216:219], v[4:7]
	v_mfma_f32_16x16x32_bf16 v[0:3], v[164:167], v[216:219], v[0:3]
	v_mfma_f32_16x16x32_bf16 v[52:55], v[160:163], v[196:199], v[52:55]
	v_mfma_f32_16x16x32_bf16 v[48:51], v[168:171], v[196:199], v[48:51]
	v_mfma_f32_16x16x32_bf16 v[36:39], v[160:163], v[204:207], v[36:39]
	v_mfma_f32_16x16x32_bf16 v[32:35], v[168:171], v[204:207], v[32:35]
	v_mfma_f32_16x16x32_bf16 v[20:23], v[160:163], v[212:215], v[20:23]
	v_mfma_f32_16x16x32_bf16 v[16:19], v[168:171], v[212:215], v[16:19]
	v_mfma_f32_16x16x32_bf16 v[4:7], v[160:163], v[220:223], v[4:7]
	v_mfma_f32_16x16x32_bf16 v[0:3], v[168:171], v[220:223], v[0:3]
	s_setprio 0
	s_setprio 1
	v_mfma_f32_16x16x32_bf16 v[60:63], v[172:175], v[192:195], v[60:63]
	v_mfma_f32_16x16x32_bf16 v[56:59], v[184:187], v[192:195], v[56:59]
	v_mfma_f32_16x16x32_bf16 v[44:47], v[172:175], v[200:203], v[44:47]
	v_mfma_f32_16x16x32_bf16 v[40:43], v[184:187], v[200:203], v[40:43]
	v_mfma_f32_16x16x32_bf16 v[28:31], v[172:175], v[208:211], v[28:31]
	v_mfma_f32_16x16x32_bf16 v[24:27], v[184:187], v[208:211], v[24:27]
	v_mfma_f32_16x16x32_bf16 v[12:15], v[172:175], v[216:219], v[12:15]
	v_mfma_f32_16x16x32_bf16 v[8:11], v[184:187], v[216:219], v[8:11]
	v_mfma_f32_16x16x32_bf16 v[60:63], v[176:179], v[196:199], v[60:63]
	v_mfma_f32_16x16x32_bf16 v[56:59], v[188:191], v[196:199], v[56:59]
	v_mfma_f32_16x16x32_bf16 v[44:47], v[176:179], v[204:207], v[44:47]
	v_mfma_f32_16x16x32_bf16 v[40:43], v[188:191], v[204:207], v[40:43]
	v_mfma_f32_16x16x32_bf16 v[28:31], v[176:179], v[212:215], v[28:31]
	v_mfma_f32_16x16x32_bf16 v[24:27], v[188:191], v[212:215], v[24:27]
	v_mfma_f32_16x16x32_bf16 v[12:15], v[176:179], v[220:223], v[12:15]
	v_mfma_f32_16x16x32_bf16 v[8:11], v[188:191], v[220:223], v[8:11]
	s_setprio 0
	s_barrier
	s_add_i32 s49, 0, 0x18000
	v_add_u32_e32 v159, s49, v153
	s_add_i32 s50, 0, 0x1c000
	ds_read_b128 v[144:147], v159
	ds_read_b128 v[160:163], v159 offset:1024
	ds_read_b128 v[164:167], v159 offset:2048
	ds_read_b128 v[168:171], v159 offset:3072
	v_add_u32_e32 v159, s50, v153
	ds_read_b128 v[172:175], v159
	ds_read_b128 v[176:179], v159 offset:1024
	ds_read_b128 v[184:187], v159 offset:2048
	ds_read_b128 v[188:191], v159 offset:3072
	s_add_u32 s24, s24, 0x80000
	s_addc_u32 s25, s25, 0
	s_mov_b32 m0, s33
	v_lshl_add_u64 v[230:231], s[24:25], 0, v[128:129]
	ds_read_b128 v[192:195], v157 offset:32768
	ds_read_b128 v[196:199], v157 offset:33792
	ds_read_b128 v[200:203], v157 offset:34816
	ds_read_b128 v[204:207], v157 offset:35840
	ds_read_b128 v[208:211], v157 offset:36864
	ds_read_b128 v[212:215], v157 offset:37888
	ds_read_b128 v[216:219], v157 offset:38912
	ds_read_b128 v[220:223], v157 offset:39936
	global_load_lds_dwordx4 v[230:231], off
	v_lshl_add_u64 v[230:231], s[24:25], 0, v[132:133]
	s_mov_b32 m0, s34
	s_nop 0
	global_load_lds_dwordx4 v[230:231], off
	s_waitcnt vmcnt(8)
	s_waitcnt lgkmcnt(0)
	s_barrier
	s_setprio 1
	s_waitcnt lgkmcnt(0)
	v_mfma_f32_16x16x32_bf16 v[116:119], v[144:147], v[192:195], v[116:119]
	v_mfma_f32_16x16x32_bf16 v[112:115], v[164:167], v[192:195], v[112:115]
	v_mfma_f32_16x16x32_bf16 v[100:103], v[144:147], v[200:203], v[100:103]
	v_mfma_f32_16x16x32_bf16 v[96:99], v[164:167], v[200:203], v[96:99]
	v_mfma_f32_16x16x32_bf16 v[84:87], v[144:147], v[208:211], v[84:87]
	v_mfma_f32_16x16x32_bf16 v[80:83], v[164:167], v[208:211], v[80:83]
	v_mfma_f32_16x16x32_bf16 v[72:75], v[144:147], v[216:219], v[72:75]
	v_mfma_f32_16x16x32_bf16 v[64:67], v[164:167], v[216:219], v[64:67]
	v_mfma_f32_16x16x32_bf16 v[116:119], v[160:163], v[196:199], v[116:119]
	v_mfma_f32_16x16x32_bf16 v[112:115], v[168:171], v[196:199], v[112:115]
	v_mfma_f32_16x16x32_bf16 v[100:103], v[160:163], v[204:207], v[100:103]
	v_mfma_f32_16x16x32_bf16 v[96:99], v[168:171], v[204:207], v[96:99]
	v_mfma_f32_16x16x32_bf16 v[84:87], v[160:163], v[212:215], v[84:87]
	v_mfma_f32_16x16x32_bf16 v[80:83], v[168:171], v[212:215], v[80:83]
	v_mfma_f32_16x16x32_bf16 v[72:75], v[160:163], v[220:223], v[72:75]
	v_mfma_f32_16x16x32_bf16 v[64:67], v[168:171], v[220:223], v[64:67]
	s_setprio 0
	s_setprio 1
	v_mfma_f32_16x16x32_bf16 v[124:127], v[172:175], v[192:195], v[124:127]
	v_mfma_f32_16x16x32_bf16 v[120:123], v[184:187], v[192:195], v[120:123]
	v_mfma_f32_16x16x32_bf16 v[108:111], v[172:175], v[200:203], v[108:111]
	v_mfma_f32_16x16x32_bf16 v[104:107], v[184:187], v[200:203], v[104:107]
	v_mfma_f32_16x16x32_bf16 v[92:95], v[172:175], v[208:211], v[92:95]
	v_mfma_f32_16x16x32_bf16 v[88:91], v[184:187], v[208:211], v[88:91]
	v_mfma_f32_16x16x32_bf16 v[76:79], v[172:175], v[216:219], v[76:79]
	v_mfma_f32_16x16x32_bf16 v[68:71], v[184:187], v[216:219], v[68:71]
	v_mfma_f32_16x16x32_bf16 v[124:127], v[176:179], v[196:199], v[124:127]
	v_mfma_f32_16x16x32_bf16 v[120:123], v[188:191], v[196:199], v[120:123]
	v_mfma_f32_16x16x32_bf16 v[108:111], v[176:179], v[204:207], v[108:111]
	v_mfma_f32_16x16x32_bf16 v[104:107], v[188:191], v[204:207], v[104:107]
	v_mfma_f32_16x16x32_bf16 v[92:95], v[176:179], v[212:215], v[92:95]
	v_mfma_f32_16x16x32_bf16 v[88:91], v[188:191], v[212:215], v[88:91]
	v_mfma_f32_16x16x32_bf16 v[76:79], v[176:179], v[220:223], v[76:79]
	v_mfma_f32_16x16x32_bf16 v[68:71], v[188:191], v[220:223], v[68:71]
	s_setprio 0
	s_barrier
	s_add_i32 s24, s49, s29
	v_lshl_add_u64 v[180:181], v[180:181], 0, s[8:9]
	s_mov_b32 m0, s24
	ds_read_b128 v[192:195], v157 offset:49152
	ds_read_b128 v[196:199], v157 offset:50176
	ds_read_b128 v[200:203], v157 offset:51200
	ds_read_b128 v[204:207], v157 offset:52224
	ds_read_b128 v[208:211], v157 offset:53248
	ds_read_b128 v[212:215], v157 offset:54272
	ds_read_b128 v[216:219], v157 offset:55296
	ds_read_b128 v[220:223], v157 offset:56320
	global_load_lds_dwordx4 v[180:181], off
	s_add_i32 m0, s24, 0x2000
	s_add_u32 s22, s22, 0x80080
	v_lshl_add_u64 v[180:181], v[224:225], 0, s[8:9]
	s_addc_u32 s23, s23, 0
	s_add_i32 s24, s50, s29
	global_load_lds_dwordx4 v[180:181], off
	v_lshl_add_u64 v[180:181], s[22:23], 0, v[130:131]
	s_mov_b32 m0, s24
	s_nop 0
	global_load_lds_dwordx4 v[180:181], off
	v_lshl_add_u64 v[180:181], s[22:23], 0, v[134:135]
	s_add_i32 m0, s24, 0x2000
	s_nop 0
	global_load_lds_dwordx4 v[180:181], off
	v_lshl_add_u64 v[180:181], v[226:227], 0, s[8:9]
	s_mov_b32 m0, s36
	s_nop 0
	global_load_lds_dwordx4 v[180:181], off
	v_lshl_add_u64 v[180:181], v[228:229], 0, s[8:9]
	s_mov_b32 m0, s37
	s_nop 0
	global_load_lds_dwordx4 v[180:181], off
	s_waitcnt vmcnt(8)
	s_waitcnt lgkmcnt(0)
	s_barrier
	s_setprio 1
	s_waitcnt lgkmcnt(0)
	v_mfma_f32_16x16x32_bf16 v[52:55], v[144:147], v[192:195], v[52:55]
	v_mfma_f32_16x16x32_bf16 v[48:51], v[164:167], v[192:195], v[48:51]
	v_mfma_f32_16x16x32_bf16 v[36:39], v[144:147], v[200:203], v[36:39]
	v_mfma_f32_16x16x32_bf16 v[32:35], v[164:167], v[200:203], v[32:35]
	v_mfma_f32_16x16x32_bf16 v[20:23], v[144:147], v[208:211], v[20:23]
	v_mfma_f32_16x16x32_bf16 v[16:19], v[164:167], v[208:211], v[16:19]
	v_mfma_f32_16x16x32_bf16 v[4:7], v[144:147], v[216:219], v[4:7]
	v_mfma_f32_16x16x32_bf16 v[0:3], v[164:167], v[216:219], v[0:3]
	v_mfma_f32_16x16x32_bf16 v[52:55], v[160:163], v[196:199], v[52:55]
	v_mfma_f32_16x16x32_bf16 v[48:51], v[168:171], v[196:199], v[48:51]
	v_mfma_f32_16x16x32_bf16 v[36:39], v[160:163], v[204:207], v[36:39]
	v_mfma_f32_16x16x32_bf16 v[32:35], v[168:171], v[204:207], v[32:35]
	v_mfma_f32_16x16x32_bf16 v[20:23], v[160:163], v[212:215], v[20:23]
	v_mfma_f32_16x16x32_bf16 v[16:19], v[168:171], v[212:215], v[16:19]
	v_mfma_f32_16x16x32_bf16 v[4:7], v[160:163], v[220:223], v[4:7]
	v_mfma_f32_16x16x32_bf16 v[0:3], v[168:171], v[220:223], v[0:3]
	s_setprio 0
	s_setprio 1
	v_mfma_f32_16x16x32_bf16 v[60:63], v[172:175], v[192:195], v[60:63]
	v_mfma_f32_16x16x32_bf16 v[56:59], v[184:187], v[192:195], v[56:59]
	s_add_i32 s48, s48, 2
	s_add_u32 s20, s20, 0x100
	s_addc_u32 s21, s21, 0
	s_add_u32 s46, s46, 0x100
	s_addc_u32 s47, s47, 0
	s_cmp_gt_u32 s48, 29
	v_mfma_f32_16x16x32_bf16 v[44:47], v[172:175], v[200:203], v[44:47]
	v_mfma_f32_16x16x32_bf16 v[40:43], v[184:187], v[200:203], v[40:43]
	v_mfma_f32_16x16x32_bf16 v[28:31], v[172:175], v[208:211], v[28:31]
	v_mfma_f32_16x16x32_bf16 v[24:27], v[184:187], v[208:211], v[24:27]
	v_mfma_f32_16x16x32_bf16 v[12:15], v[172:175], v[216:219], v[12:15]
	v_mfma_f32_16x16x32_bf16 v[8:11], v[184:187], v[216:219], v[8:11]
	v_mfma_f32_16x16x32_bf16 v[60:63], v[176:179], v[196:199], v[60:63]
	v_mfma_f32_16x16x32_bf16 v[56:59], v[188:191], v[196:199], v[56:59]
	v_mfma_f32_16x16x32_bf16 v[44:47], v[176:179], v[204:207], v[44:47]
	v_mfma_f32_16x16x32_bf16 v[40:43], v[188:191], v[204:207], v[40:43]
	v_mfma_f32_16x16x32_bf16 v[28:31], v[176:179], v[212:215], v[28:31]
	v_mfma_f32_16x16x32_bf16 v[24:27], v[188:191], v[212:215], v[24:27]
	v_mfma_f32_16x16x32_bf16 v[12:15], v[176:179], v[220:223], v[12:15]
	v_mfma_f32_16x16x32_bf16 v[8:11], v[188:191], v[220:223], v[8:11]
	s_setprio 0
	s_barrier
	s_cbranch_scc0 .LBB0_2311
	s_and_b64 vcc, exec, s[10:11]
	s_cbranch_vccz .LBB0_2314
	s_barrier

.LBB0_2393:
	ds_read_b128 v[140:143], v147
	ds_read_b128 v[154:157], v147 offset:1024
	ds_read_b128 v[158:161], v147 offset:2048
	ds_read_b128 v[162:165], v147 offset:3072
	ds_read_b128 v[166:169], v152
	ds_read_b128 v[170:173], v152 offset:1024
	ds_read_b128 v[174:177], v152 offset:2048
	ds_read_b128 v[178:181], v152 offset:3072
	s_add_u32 s20, s18, 0x100
	s_addc_u32 s21, s19, 0
	s_cmpk_eq_i32 s46, 0x54
	s_cselect_b32 s25, s1, s21
	s_cselect_b32 s24, s0, s20
	s_cselect_b32 s23, s17, s45
	s_cselect_b32 s22, s16, s44
	v_lshl_add_u64 v[216:217], s[18:19], 0, v[132:133]
	s_add_i32 m0, s27, 0xc000
	ds_read_b128 v[184:187], v153
	ds_read_b128 v[188:191], v153 offset:1024
	ds_read_b128 v[192:195], v153 offset:2048
	ds_read_b128 v[196:199], v153 offset:3072
	ds_read_b128 v[200:203], v153 offset:4096
	ds_read_b128 v[204:207], v153 offset:5120
	ds_read_b128 v[208:211], v153 offset:6144
	ds_read_b128 v[212:215], v153 offset:7168
	global_load_lds_dwordx4 v[216:217], off
	v_lshl_add_u64 v[216:217], s[18:19], 0, v[134:135]
	s_add_i32 m0, s27, 0xe000
	s_nop 0
	global_load_lds_dwordx4 v[216:217], off
	s_waitcnt vmcnt(8)
	s_waitcnt lgkmcnt(0)
	s_barrier
	s_setprio 1
	s_waitcnt lgkmcnt(0)
	v_mfma_f32_16x16x32_bf16 v[124:127], v[140:143], v[184:187], v[124:127]
	v_mfma_f32_16x16x32_bf16 v[120:123], v[158:161], v[184:187], v[120:123]
	v_mfma_f32_16x16x32_bf16 v[108:111], v[140:143], v[192:195], v[108:111]
	v_mfma_f32_16x16x32_bf16 v[104:107], v[158:161], v[192:195], v[104:107]
	v_mfma_f32_16x16x32_bf16 v[92:95], v[140:143], v[200:203], v[92:95]
	v_mfma_f32_16x16x32_bf16 v[88:91], v[158:161], v[200:203], v[88:91]
	v_mfma_f32_16x16x32_bf16 v[76:79], v[140:143], v[208:211], v[76:79]
	v_mfma_f32_16x16x32_bf16 v[72:75], v[158:161], v[208:211], v[72:75]
	v_mfma_f32_16x16x32_bf16 v[124:127], v[154:157], v[188:191], v[124:127]
	v_mfma_f32_16x16x32_bf16 v[120:123], v[162:165], v[188:191], v[120:123]
	v_mfma_f32_16x16x32_bf16 v[108:111], v[154:157], v[196:199], v[108:111]
	v_mfma_f32_16x16x32_bf16 v[104:107], v[162:165], v[196:199], v[104:107]
	v_mfma_f32_16x16x32_bf16 v[92:95], v[154:157], v[204:207], v[92:95]
	v_mfma_f32_16x16x32_bf16 v[88:91], v[162:165], v[204:207], v[88:91]
	v_mfma_f32_16x16x32_bf16 v[76:79], v[154:157], v[212:215], v[76:79]
	v_mfma_f32_16x16x32_bf16 v[72:75], v[162:165], v[212:215], v[72:75]
	s_setprio 0
	s_setprio 1
	v_mfma_f32_16x16x32_bf16 v[116:119], v[166:169], v[184:187], v[116:119]
	v_mfma_f32_16x16x32_bf16 v[112:115], v[174:177], v[184:187], v[112:115]
	v_mfma_f32_16x16x32_bf16 v[100:103], v[166:169], v[192:195], v[100:103]
	v_mfma_f32_16x16x32_bf16 v[96:99], v[174:177], v[192:195], v[96:99]
	v_mfma_f32_16x16x32_bf16 v[84:87], v[166:169], v[200:203], v[84:87]
	v_mfma_f32_16x16x32_bf16 v[80:83], v[174:177], v[200:203], v[80:83]
	v_mfma_f32_16x16x32_bf16 v[68:71], v[166:169], v[208:211], v[68:71]
	v_mfma_f32_16x16x32_bf16 v[64:67], v[174:177], v[208:211], v[64:67]
	v_mfma_f32_16x16x32_bf16 v[116:119], v[170:173], v[188:191], v[116:119]
	v_mfma_f32_16x16x32_bf16 v[112:115], v[178:181], v[188:191], v[112:115]
	v_mfma_f32_16x16x32_bf16 v[100:103], v[170:173], v[196:199], v[100:103]
	v_mfma_f32_16x16x32_bf16 v[96:99], v[178:181], v[196:199], v[96:99]
	v_mfma_f32_16x16x32_bf16 v[84:87], v[170:173], v[204:207], v[84:87]
	v_mfma_f32_16x16x32_bf16 v[80:83], v[178:181], v[204:207], v[80:83]
	v_mfma_f32_16x16x32_bf16 v[68:71], v[170:173], v[212:215], v[68:71]
	v_mfma_f32_16x16x32_bf16 v[64:67], v[178:181], v[212:215], v[64:67]
	s_setprio 0
	s_barrier
	s_add_i32 s18, s38, s26
	v_lshl_add_u64 v[216:217], s[22:23], 0, v[128:129]
	s_mov_b32 m0, s18
	ds_read_b128 v[184:187], v153 offset:16384
	ds_read_b128 v[188:191], v153 offset:17408
	ds_read_b128 v[192:195], v153 offset:18432
	ds_read_b128 v[196:199], v153 offset:19456
	ds_read_b128 v[200:203], v153 offset:20480
	ds_read_b128 v[204:207], v153 offset:21504
	ds_read_b128 v[208:211], v153 offset:22528
	ds_read_b128 v[212:215], v153 offset:23552
	global_load_lds_dwordx4 v[216:217], off
	s_add_i32 m0, s18, 0x2000
	s_add_u32 s18, s22, 0x160000
	v_lshl_add_u64 v[218:219], s[22:23], 0, v[130:131]
	s_addc_u32 s19, s23, 0
	s_add_i32 s47, s39, s26
	global_load_lds_dwordx4 v[218:219], off
	v_lshl_add_u64 v[220:221], s[18:19], 0, v[128:129]
	s_mov_b32 m0, s47
	v_lshl_add_u64 v[222:223], s[24:25], 0, v[130:131]
	global_load_lds_dwordx4 v[220:221], off
	v_lshl_add_u64 v[220:221], s[18:19], 0, v[130:131]
	s_add_i32 m0, s47, 0x2000
	s_nop 0
	global_load_lds_dwordx4 v[220:221], off
	v_lshl_add_u64 v[220:221], s[24:25], 0, v[128:129]
	s_mov_b32 m0, s27
	s_nop 0
	global_load_lds_dwordx4 v[220:221], off
	s_mov_b32 m0, s28
	s_nop 0
	global_load_lds_dwordx4 v[222:223], off
	s_waitcnt vmcnt(8)
	s_waitcnt lgkmcnt(0)
	s_barrier
	s_setprio 1
	s_waitcnt lgkmcnt(0)
	v_mfma_f32_16x16x32_bf16 v[60:63], v[140:143], v[184:187], v[60:63]
	v_mfma_f32_16x16x32_bf16 v[56:59], v[158:161], v[184:187], v[56:59]
	v_mfma_f32_16x16x32_bf16 v[44:47], v[140:143], v[192:195], v[44:47]
	v_mfma_f32_16x16x32_bf16 v[40:43], v[158:161], v[192:195], v[40:43]
	v_mfma_f32_16x16x32_bf16 v[28:31], v[140:143], v[200:203], v[28:31]
	v_mfma_f32_16x16x32_bf16 v[24:27], v[158:161], v[200:203], v[24:27]
	v_mfma_f32_16x16x32_bf16 v[12:15], v[140:143], v[208:211], v[12:15]
	v_mfma_f32_16x16x32_bf16 v[8:11], v[158:161], v[208:211], v[8:11]
	v_mfma_f32_16x16x32_bf16 v[60:63], v[154:157], v[188:191], v[60:63]
	v_mfma_f32_16x16x32_bf16 v[56:59], v[162:165], v[188:191], v[56:59]
	v_mfma_f32_16x16x32_bf16 v[44:47], v[154:157], v[196:199], v[44:47]
	v_mfma_f32_16x16x32_bf16 v[40:43], v[162:165], v[196:199], v[40:43]
	v_mfma_f32_16x16x32_bf16 v[28:31], v[154:157], v[204:207], v[28:31]
	v_mfma_f32_16x16x32_bf16 v[24:27], v[162:165], v[204:207], v[24:27]
	v_mfma_f32_16x16x32_bf16 v[12:15], v[154:157], v[212:215], v[12:15]
	v_mfma_f32_16x16x32_bf16 v[8:11], v[162:165], v[212:215], v[8:11]
	s_setprio 0
	s_setprio 1
	v_mfma_f32_16x16x32_bf16 v[52:55], v[166:169], v[184:187], v[52:55]
	v_mfma_f32_16x16x32_bf16 v[48:51], v[174:177], v[184:187], v[48:51]
	v_mfma_f32_16x16x32_bf16 v[36:39], v[166:169], v[192:195], v[36:39]
	v_mfma_f32_16x16x32_bf16 v[32:35], v[174:177], v[192:195], v[32:35]
	v_mfma_f32_16x16x32_bf16 v[20:23], v[166:169], v[200:203], v[20:23]
	v_mfma_f32_16x16x32_bf16 v[16:19], v[174:177], v[200:203], v[16:19]
	v_mfma_f32_16x16x32_bf16 v[4:7], v[166:169], v[208:211], v[4:7]
	v_mfma_f32_16x16x32_bf16 v[0:3], v[174:177], v[208:211], v[0:3]
	v_mfma_f32_16x16x32_bf16 v[52:55], v[170:173], v[188:191], v[52:55]
	v_mfma_f32_16x16x32_bf16 v[48:51], v[178:181], v[188:191], v[48:51]
	v_mfma_f32_16x16x32_bf16 v[36:39], v[170:173], v[196:199], v[36:39]
	v_mfma_f32_16x16x32_bf16 v[32:35], v[178:181], v[196:199], v[32:35]
	v_mfma_f32_16x16x32_bf16 v[20:23], v[170:173], v[204:207], v[20:23]
	v_mfma_f32_16x16x32_bf16 v[16:19], v[178:181], v[204:207], v[16:19]
	v_mfma_f32_16x16x32_bf16 v[4:7], v[170:173], v[212:215], v[4:7]
	v_mfma_f32_16x16x32_bf16 v[0:3], v[178:181], v[212:215], v[0:3]
	s_setprio 0
	s_barrier
	s_add_i32 s47, 0, 0x18000
	s_add_i32 s48, 0, 0x1c000
	v_add_u32_e32 v162, s47, v145
	v_add_u32_e32 v178, s48, v145
	ds_read_b128 v[140:143], v162
	ds_read_b128 v[154:157], v162 offset:1024
	ds_read_b128 v[158:161], v162 offset:2048
	ds_read_b128 v[162:165], v162 offset:3072
	ds_read_b128 v[166:169], v178
	ds_read_b128 v[170:173], v178 offset:1024
	ds_read_b128 v[174:177], v178 offset:2048
	ds_read_b128 v[178:181], v178 offset:3072
	s_add_u32 s18, s24, 0x160000
	s_addc_u32 s19, s25, 0
	s_mov_b32 m0, s29
	v_lshl_add_u64 v[224:225], s[18:19], 0, v[128:129]
	ds_read_b128 v[184:187], v153 offset:32768
	ds_read_b128 v[188:191], v153 offset:33792
	ds_read_b128 v[192:195], v153 offset:34816
	ds_read_b128 v[196:199], v153 offset:35840
	ds_read_b128 v[200:203], v153 offset:36864
	ds_read_b128 v[204:207], v153 offset:37888
	ds_read_b128 v[208:211], v153 offset:38912
	ds_read_b128 v[212:215], v153 offset:39936
	global_load_lds_dwordx4 v[224:225], off
	v_lshl_add_u64 v[224:225], s[18:19], 0, v[130:131]
	s_mov_b32 m0, s30
	s_nop 0
	global_load_lds_dwordx4 v[224:225], off
	s_waitcnt vmcnt(8)
	s_waitcnt lgkmcnt(0)
	s_barrier
	s_setprio 1
	s_waitcnt lgkmcnt(0)
	v_mfma_f32_16x16x32_bf16 v[124:127], v[140:143], v[184:187], v[124:127]
	v_mfma_f32_16x16x32_bf16 v[120:123], v[158:161], v[184:187], v[120:123]
	v_mfma_f32_16x16x32_bf16 v[108:111], v[140:143], v[192:195], v[108:111]
	v_mfma_f32_16x16x32_bf16 v[104:107], v[158:161], v[192:195], v[104:107]
	v_mfma_f32_16x16x32_bf16 v[92:95], v[140:143], v[200:203], v[92:95]
	v_mfma_f32_16x16x32_bf16 v[88:91], v[158:161], v[200:203], v[88:91]
	v_mfma_f32_16x16x32_bf16 v[76:79], v[140:143], v[208:211], v[76:79]
	v_mfma_f32_16x16x32_bf16 v[72:75], v[158:161], v[208:211], v[72:75]
	v_mfma_f32_16x16x32_bf16 v[124:127], v[154:157], v[188:191], v[124:127]
	v_mfma_f32_16x16x32_bf16 v[120:123], v[162:165], v[188:191], v[120:123]
	v_mfma_f32_16x16x32_bf16 v[108:111], v[154:157], v[196:199], v[108:111]
	v_mfma_f32_16x16x32_bf16 v[104:107], v[162:165], v[196:199], v[104:107]
	v_mfma_f32_16x16x32_bf16 v[92:95], v[154:157], v[204:207], v[92:95]
	v_mfma_f32_16x16x32_bf16 v[88:91], v[162:165], v[204:207], v[88:91]
	v_mfma_f32_16x16x32_bf16 v[76:79], v[154:157], v[212:215], v[76:79]
	v_mfma_f32_16x16x32_bf16 v[72:75], v[162:165], v[212:215], v[72:75]
	s_setprio 0
	s_setprio 1
	v_mfma_f32_16x16x32_bf16 v[116:119], v[166:169], v[184:187], v[116:119]
	v_mfma_f32_16x16x32_bf16 v[112:115], v[174:177], v[184:187], v[112:115]
	v_mfma_f32_16x16x32_bf16 v[100:103], v[166:169], v[192:195], v[100:103]
	v_mfma_f32_16x16x32_bf16 v[96:99], v[174:177], v[192:195], v[96:99]
	v_mfma_f32_16x16x32_bf16 v[84:87], v[166:169], v[200:203], v[84:87]
	v_mfma_f32_16x16x32_bf16 v[80:83], v[174:177], v[200:203], v[80:83]
	v_mfma_f32_16x16x32_bf16 v[68:71], v[166:169], v[208:211], v[68:71]
	v_mfma_f32_16x16x32_bf16 v[64:67], v[174:177], v[208:211], v[64:67]
	v_mfma_f32_16x16x32_bf16 v[116:119], v[170:173], v[188:191], v[116:119]
	v_mfma_f32_16x16x32_bf16 v[112:115], v[178:181], v[188:191], v[112:115]
	v_mfma_f32_16x16x32_bf16 v[100:103], v[170:173], v[196:199], v[100:103]
	v_mfma_f32_16x16x32_bf16 v[96:99], v[178:181], v[196:199], v[96:99]
	v_mfma_f32_16x16x32_bf16 v[84:87], v[170:173], v[204:207], v[84:87]
	v_mfma_f32_16x16x32_bf16 v[80:83], v[178:181], v[204:207], v[80:83]
	v_mfma_f32_16x16x32_bf16 v[68:71], v[170:173], v[212:215], v[68:71]
	v_mfma_f32_16x16x32_bf16 v[64:67], v[178:181], v[212:215], v[64:67]
	s_setprio 0
	s_barrier
	s_add_i32 s18, s47, s26
	v_lshl_add_u64 v[216:217], v[216:217], 0, s[12:13]
	s_mov_b32 m0, s18
	ds_read_b128 v[184:187], v153 offset:49152
	ds_read_b128 v[188:191], v153 offset:50176
	ds_read_b128 v[192:195], v153 offset:51200
	ds_read_b128 v[196:199], v153 offset:52224
	ds_read_b128 v[200:203], v153 offset:53248
	ds_read_b128 v[204:207], v153 offset:54272
	ds_read_b128 v[208:211], v153 offset:55296
	ds_read_b128 v[212:215], v153 offset:56320
	global_load_lds_dwordx4 v[216:217], off
	s_add_i32 m0, s18, 0x2000
	s_add_u32 s18, s22, 0x160080
	v_lshl_add_u64 v[216:217], v[218:219], 0, s[12:13]
	s_addc_u32 s19, s23, 0
	s_add_i32 s22, s48, s26
	global_load_lds_dwordx4 v[216:217], off
	v_lshl_add_u64 v[216:217], s[18:19], 0, v[128:129]
	s_mov_b32 m0, s22
	s_nop 0
	global_load_lds_dwordx4 v[216:217], off
	v_lshl_add_u64 v[216:217], s[18:19], 0, v[130:131]
	s_add_i32 m0, s22, 0x2000
	s_nop 0
	global_load_lds_dwordx4 v[216:217], off
	v_lshl_add_u64 v[216:217], v[220:221], 0, s[12:13]
	s_mov_b32 m0, s33
	s_nop 0
	global_load_lds_dwordx4 v[216:217], off
	v_lshl_add_u64 v[216:217], v[222:223], 0, s[12:13]
	s_mov_b32 m0, s34
	s_nop 0
	global_load_lds_dwordx4 v[216:217], off
	s_waitcnt vmcnt(8)
	s_waitcnt lgkmcnt(0)
	s_barrier
	s_setprio 1
	s_waitcnt lgkmcnt(0)
	v_mfma_f32_16x16x32_bf16 v[60:63], v[140:143], v[184:187], v[60:63]
	v_mfma_f32_16x16x32_bf16 v[56:59], v[158:161], v[184:187], v[56:59]
	v_mfma_f32_16x16x32_bf16 v[44:47], v[140:143], v[192:195], v[44:47]
	v_mfma_f32_16x16x32_bf16 v[40:43], v[158:161], v[192:195], v[40:43]
	v_mfma_f32_16x16x32_bf16 v[28:31], v[140:143], v[200:203], v[28:31]
	v_mfma_f32_16x16x32_bf16 v[24:27], v[158:161], v[200:203], v[24:27]
	v_mfma_f32_16x16x32_bf16 v[12:15], v[140:143], v[208:211], v[12:15]
	v_mfma_f32_16x16x32_bf16 v[8:11], v[158:161], v[208:211], v[8:11]
	v_mfma_f32_16x16x32_bf16 v[60:63], v[154:157], v[188:191], v[60:63]
	v_mfma_f32_16x16x32_bf16 v[56:59], v[162:165], v[188:191], v[56:59]
	v_mfma_f32_16x16x32_bf16 v[44:47], v[154:157], v[196:199], v[44:47]
	v_mfma_f32_16x16x32_bf16 v[40:43], v[162:165], v[196:199], v[40:43]
	v_mfma_f32_16x16x32_bf16 v[28:31], v[154:157], v[204:207], v[28:31]
	v_mfma_f32_16x16x32_bf16 v[24:27], v[162:165], v[204:207], v[24:27]
	v_mfma_f32_16x16x32_bf16 v[12:15], v[154:157], v[212:215], v[12:15]
	v_mfma_f32_16x16x32_bf16 v[8:11], v[162:165], v[212:215], v[8:11]
	s_setprio 0
	s_setprio 1
	v_mfma_f32_16x16x32_bf16 v[52:55], v[166:169], v[184:187], v[52:55]
	v_mfma_f32_16x16x32_bf16 v[48:51], v[174:177], v[184:187], v[48:51]
	s_add_i32 s46, s46, 2
	s_add_u32 s44, s44, 0x100
	s_addc_u32 s45, s45, 0
	s_cmpk_gt_u32 s46, 0x55
	s_mov_b64 s[18:19], s[20:21]
	v_mfma_f32_16x16x32_bf16 v[36:39], v[166:169], v[192:195], v[36:39]
	v_mfma_f32_16x16x32_bf16 v[32:35], v[174:177], v[192:195], v[32:35]
	v_mfma_f32_16x16x32_bf16 v[20:23], v[166:169], v[200:203], v[20:23]
	v_mfma_f32_16x16x32_bf16 v[16:19], v[174:177], v[200:203], v[16:19]
	v_mfma_f32_16x16x32_bf16 v[4:7], v[166:169], v[208:211], v[4:7]
	v_mfma_f32_16x16x32_bf16 v[0:3], v[174:177], v[208:211], v[0:3]
	v_mfma_f32_16x16x32_bf16 v[52:55], v[170:173], v[188:191], v[52:55]
	v_mfma_f32_16x16x32_bf16 v[48:51], v[178:181], v[188:191], v[48:51]
	v_mfma_f32_16x16x32_bf16 v[36:39], v[170:173], v[196:199], v[36:39]
	v_mfma_f32_16x16x32_bf16 v[32:35], v[178:181], v[196:199], v[32:35]
	v_mfma_f32_16x16x32_bf16 v[20:23], v[170:173], v[204:207], v[20:23]
	v_mfma_f32_16x16x32_bf16 v[16:19], v[178:181], v[204:207], v[16:19]
	v_mfma_f32_16x16x32_bf16 v[4:7], v[170:173], v[212:215], v[4:7]
	v_mfma_f32_16x16x32_bf16 v[0:3], v[178:181], v[212:215], v[0:3]
	s_setprio 0
	s_barrier
	s_cbranch_scc0 .LBB0_2393
	s_and_b64 vcc, exec, s[14:15]
	s_cbranch_vccz .LBB0_2396
	s_barrier
